# v014 + G2 residual epilogue: pairs of 8-byte bf16 write-through stores merged into 16-byte stores via permlane32/16 swaps
# speedup vs baseline: 1.0135x; 1.0135x over previous
; __device__ __forceinline__ unsigned cvt_pk_bf16(float lo, float hi) { unsigned r; asm volatile("v_cvt_pk_bf16_f32 %0, %1, %2" : "=v"(r) : "v"(lo), "v"(hi)); return r; }
; __device__ __forceinline__ void st_wt8(void* ptr, u32x2 v) { asm volatile("global_store_dwordx2 %0, %1, off sc1" :: "v"(ptr), "v"(v) : "memory"); }
; __device__ __forceinline__ void st_wt4(void* ptr, unsigned v) { asm volatile("global_store_dword %0, %1, off sc1" :: "v"(ptr), "v"(v) : "memory"); }
;     __device__ __forceinline__ void operator()(const f32x4 (&acc)[2][2][4][2], const pg8::Unit& u, int wr, int wc, int fr, int fq) const {
;         const int row0 = u.pm * 256 + wr * 64 + fr, col0 = u.pn * 256 + wc * 32 + 4 * fq;
; #pragma unroll
;         for (int ai = 0; ai < 2; ++ai)
; #pragma unroll
;             for (int m = 0; m < 4; ++m) {
;                 const int row = row0 + ai * 128 + m * 16;
;                 float* orow = oy + (size_t)row * DM + col0;
;                 const float* xr = FIRST ? ((row < MP ? xp + (size_t)row * DM : xs + (size_t)(row - MP) * DM) + col0) : orow;
;                 float q = 0.f;
; #pragma unroll
;                 for (int bj = 0; bj < 2; ++bj)
; #pragma unroll
;                     for (int n = 0; n < 2; ++n) {
;                         const f32x4 xv = *(const f32x4*)(xr + bj * 128 + n * 16);
;                         const f32x4 o = xv + acc[ai][bj][m][n];
;                         *(f32x4*)(orow + bj * 128 + n * 16) = o;
;                         q += (o[0] * o[0] + o[1] * o[1]) + (o[2] * o[2] + o[3] * o[3]);
;                         if (FIRST) { u32x2 w; w.x = cvt_pk_bf16(o[0], o[1]); w.y = cvt_pk_bf16(o[2], o[3]); st_wt8(xb + (size_t)row * DM + col0 + bj * 128 + n * 16, w); }
;                     }
;                 q += __shfl_xor(q, 16); q += __shfl_xor(q, 32);
;                 if (fq == 0) { if (FIRST) st_wt4(ss + (size_t)row * 32 + u.pn * 4 + wc, __float_as_uint(q)); else ss[(size_t)row * 32 + u.pn * 4 + wc] = q; }
;             }
.LBB0_299:
	v_mbcnt_lo_u32_b32 v240, -1, 0
	v_mbcnt_hi_u32_b32 v240, -1, v240
	v_lshrrev_b32_e32 v240, 4, v240
	v_lshlrev_b32_e32 v240, 3, v240
	v_add_u32_e32 v240, 0xffffffe0, v240
	v_mov_b32_e32 v241, -1
	v_lshl_add_u32 v144, s63, 8, v148
	v_ashrrev_i32_e32 v145, 31, v144
	v_readlane_b32 s68, v234, 3
	v_add_u32_e32 v132, 0xffffe000, v144
	v_lshl_or_b32 v140, s10, 8, v150
	v_lshlrev_b64 v[156:157], 13, v[144:145]
	v_readlane_b32 s69, v234, 4
	v_readlane_b32 s70, v234, 5
	v_readlane_b32 s71, v234, 6
	v_lshlrev_b64 v[154:155], 13, v[132:133]
	v_ashrrev_i32_e32 v141, 31, v140
	v_lshl_add_u64 v[152:153], s[68:69], 0, v[156:157]
	v_lshl_add_u64 v[154:155], s[70:71], 0, v[154:155]
	v_cmp_gt_i32_e32 vcc, s54, v144
	v_lshlrev_b64 v[142:143], 2, v[140:141]
	v_lshlrev_b64 v[160:161], 12, v[144:145]
	v_cndmask_b32_e32 v153, v155, v153, vcc
	v_cndmask_b32_e32 v152, v154, v152, vcc
	v_lshl_add_u64 v[158:159], v[152:153], 0, v[142:143]
	v_mov_b32_e32 v232, v158
	v_mov_b32_e32 v233, v159
	global_load_dwordx4 v[164:167], v[232:233], off
	global_load_dwordx4 v[168:171], v[232:233], off offset:64
	global_load_dwordx4 v[172:175], v[232:233], off offset:512
	global_load_dwordx4 v[176:179], v[232:233], off offset:576
	s_mov_b64 s[98:99], 0x20000
	v_lshl_add_u64 v[192:193], v[232:233], 0, s[98:99]
	global_load_dwordx4 v[180:183], v[192:193], off
	global_load_dwordx4 v[184:187], v[192:193], off offset:64
	global_load_dwordx4 v[188:191], v[192:193], off offset:512
	global_load_dwordx4 v[196:199], v[192:193], off offset:576
	s_mov_b64 s[98:99], 0x40000
	v_lshl_add_u64 v[192:193], v[232:233], 0, s[98:99]
	global_load_dwordx4 v[200:203], v[192:193], off
	global_load_dwordx4 v[204:207], v[192:193], off offset:64
	global_load_dwordx4 v[208:211], v[192:193], off offset:512
	global_load_dwordx4 v[212:215], v[192:193], off offset:576
	s_mov_b64 s[98:99], 0x60000
	v_lshl_add_u64 v[192:193], v[232:233], 0, s[98:99]
	global_load_dwordx4 v[216:219], v[192:193], off
	global_load_dwordx4 v[220:223], v[192:193], off offset:64
	global_load_dwordx4 v[224:227], v[192:193], off offset:512
	global_load_dwordx4 v[228:231], v[192:193], off offset:576
	s_waitcnt vmcnt(0)
	v_mov_b32_e32 v152, v164
	v_mov_b32_e32 v153, v165
	v_mov_b32_e32 v154, v166
	v_mov_b32_e32 v155, v167
	v_lshl_add_u64 v[156:157], s[84:85], 0, v[156:157]
	v_lshl_add_u64 v[160:161], s[20:21], 0, v[160:161]
	v_lshl_add_u64 v[162:163], v[156:157], 0, v[142:143]
	v_lshl_add_u64 v[160:161], v[140:141], 1, v[160:161]
	v_lshl_add_u64 v[156:157], v[160:161], 0, 32
	s_lshl_b32 s42, s10, 2
	s_ashr_i32 s43, s42, 31
	v_readlane_b32 s72, v234, 7
	v_readlane_b32 s73, v234, 8
	v_readlane_b32 s74, v234, 9
	v_readlane_b32 s75, v234, 10
	v_readlane_b32 s76, v234, 11
	v_readlane_b32 s77, v234, 12
	v_readlane_b32 s78, v234, 13
	v_readlane_b32 s79, v234, 14
	v_readlane_b32 s80, v234, 15
	v_readlane_b32 s81, v234, 16
	v_readlane_b32 s82, v234, 17
	v_readlane_b32 s83, v234, 18
	v_pk_add_f32 v[126:127], v[126:127], v[154:155]
	v_pk_add_f32 v[124:125], v[124:125], v[152:153]
	global_store_dwordx4 v[162:163], v[124:127], off
	v_cvt_pk_bf16_f32 v236, v124, v125
	v_cvt_pk_bf16_f32 v237, v126, v127
	s_nop 0
	v_mov_b32_e32 v152, v168
	v_mov_b32_e32 v153, v169
	v_mov_b32_e32 v154, v170
	v_mov_b32_e32 v155, v171
	v_pk_add_f32 v[122:123], v[122:123], v[154:155]
	v_pk_add_f32 v[120:121], v[120:121], v[152:153]
	global_store_dwordx4 v[162:163], v[120:123], off offset:64
	v_cvt_pk_bf16_f32 v238, v120, v121
	v_cvt_pk_bf16_f32 v239, v122, v123
	s_nop 0
	s_nop 1
	v_permlane32_swap_b32_e32 v236, v238
	v_permlane32_swap_b32_e32 v237, v239
	s_nop 1
	v_permlane16_swap_b32_e32 v236, v238
	v_permlane16_swap_b32_e32 v237, v239
	v_lshl_add_u64 v[242:243], v[156:157], 0, v[240:241]
	s_nop 0
	global_store_dwordx4 v[242:243], v[236:239], off sc1
	s_nop 1
	v_mov_b32_e32 v152, v172
	v_mov_b32_e32 v153, v173
	v_mov_b32_e32 v154, v174
	v_mov_b32_e32 v155, v175
	v_lshl_add_u64 v[156:157], v[160:161], 0, s[28:29]
	v_pk_add_f32 v[154:155], v[118:119], v[154:155]
	v_pk_add_f32 v[152:153], v[116:117], v[152:153]
	global_store_dwordx4 v[162:163], v[152:155], off offset:512
	v_cvt_pk_bf16_f32 v236, v152, v153
	v_cvt_pk_bf16_f32 v237, v154, v155
	v_xor_b32_e32 v118, 32, v195
	v_mov_b32_e32 v156, v176
	v_mov_b32_e32 v157, v177
	v_mov_b32_e32 v158, v178
	v_mov_b32_e32 v159, v179
	v_and_b32_e32 v117, 64, v195
	v_xor_b32_e32 v116, 16, v195
	v_add_u32_e32 v117, 64, v117
	v_cmp_lt_i32_e32 vcc, v116, v117
	v_mul_f32_e32 v119, v127, v127
	v_fmac_f32_e32 v119, v126, v126
	v_cndmask_b32_e32 v116, v195, v116, vcc
	v_cmp_lt_i32_e32 vcc, v118, v117
	v_lshlrev_b32_e32 v116, 2, v116
	v_pk_add_f32 v[114:115], v[114:115], v[158:159]
	v_cndmask_b32_e32 v117, v195, v118, vcc
	v_mul_f32_e32 v118, v125, v125
	v_fmac_f32_e32 v118, v124, v124
	v_add_f32_e32 v118, v118, v119
	v_mul_f32_e32 v119, v121, v121
	v_mul_f32_e32 v121, v123, v123
	v_fmac_f32_e32 v119, v120, v120
	v_fmac_f32_e32 v121, v122, v122
	v_add_f32_e32 v119, v119, v121
	v_add_f32_e32 v118, v118, v119
	v_mul_f32_e32 v119, v153, v153
	v_mul_f32_e32 v120, v155, v155
	v_fmac_f32_e32 v119, v152, v152
	v_fmac_f32_e32 v120, v154, v154
	v_add_f32_e32 v119, v119, v120
	v_pk_add_f32 v[112:113], v[112:113], v[156:157]
	v_add_f32_e32 v118, v118, v119
	v_mul_f32_e32 v119, v113, v113
	v_mul_f32_e32 v120, v115, v115
	v_fmac_f32_e32 v119, v112, v112
	v_fmac_f32_e32 v120, v114, v114
	v_add_f32_e32 v119, v119, v120
	v_add_f32_e32 v122, v118, v119
	ds_bpermute_b32 v123, v116, v122
	global_store_dwordx4 v[162:163], v[112:115], off offset:576
	v_cvt_pk_bf16_f32 v238, v112, v113
	v_cvt_pk_bf16_f32 v239, v114, v115
	v_lshl_add_u64 v[118:119], v[160:161], 0, s[30:31]
	s_nop 1
	v_permlane32_swap_b32_e32 v236, v238
	v_permlane32_swap_b32_e32 v237, v239
	s_nop 1
	v_permlane16_swap_b32_e32 v236, v238
	v_permlane16_swap_b32_e32 v237, v239
	v_lshl_add_u64 v[242:243], v[118:119], 0, v[240:241]
	s_nop 0
	global_store_dwordx4 v[242:243], v[236:239], off sc1
	s_nop 1
	s_waitcnt lgkmcnt(0)
	v_add_f32_e32 v112, v122, v123
	v_lshlrev_b32_e32 v114, 2, v117
	ds_bpermute_b32 v113, v114, v112
	s_and_saveexec_b64 s[44:45], s[4:5]
	s_cbranch_execz .LBB0_301
	s_waitcnt lgkmcnt(0)
	v_add_f32_e32 v115, v112, v113
	v_lshlrev_b64 v[112:113], 7, v[144:145]
	v_lshl_add_u64 v[112:113], s[2:3], 0, v[112:113]
	v_lshl_add_u64 v[112:113], s[42:43], 2, v[112:113]
	s_lshl_b32 s10, s55, 2
	v_lshl_add_u64 v[112:113], v[112:113], 0, s[10:11]
	global_store_dword v[112:113], v115, off sc1
; __device__ __forceinline__ unsigned cvt_pk_bf16(float lo, float hi) { unsigned r; asm volatile("v_cvt_pk_bf16_f32 %0, %1, %2" : "=v"(r) : "v"(lo), "v"(hi)); return r; }
; __device__ __forceinline__ void st_wt8(void* ptr, u32x2 v) { asm volatile("global_store_dwordx2 %0, %1, off sc1" :: "v"(ptr), "v"(v) : "memory"); }
; __device__ __forceinline__ void st_wt4(void* ptr, unsigned v) { asm volatile("global_store_dword %0, %1, off sc1" :: "v"(ptr), "v"(v) : "memory"); }
;     __device__ __forceinline__ void operator()(const f32x4 (&acc)[2][2][4][2], const pg8::Unit& u, int wr, int wc, int fr, int fq) const {
;     ...
;         for (int ai = 0; ai < 2; ++ai)
; #pragma unroll
;             for (int m = 0; m < 4; ++m) {
;                 const int row = row0 + ai * 128 + m * 16;
;                 float* orow = oy + (size_t)row * DM + col0;
;                 const float* xr = FIRST ? ((row < MP ? xp + (size_t)row * DM : xs + (size_t)(row - MP) * DM) + col0) : orow;
;                 float q = 0.f;
; #pragma unroll
;                 for (int bj = 0; bj < 2; ++bj)
; #pragma unroll
;                     for (int n = 0; n < 2; ++n) {
;                         const f32x4 xv = *(const f32x4*)(xr + bj * 128 + n * 16);
;                         const f32x4 o = xv + acc[ai][bj][m][n];
;                         *(f32x4*)(orow + bj * 128 + n * 16) = o;
;                         q += (o[0] * o[0] + o[1] * o[1]) + (o[2] * o[2] + o[3] * o[3]);
;                         if (FIRST) { u32x2 w; w.x = cvt_pk_bf16(o[0], o[1]); w.y = cvt_pk_bf16(o[2], o[3]); st_wt8(xb + (size_t)row * DM + col0 + bj * 128 + n * 16, w); }
;                     }
;                 q += __shfl_xor(q, 16); q += __shfl_xor(q, 32);
;                 if (fq == 0) { if (FIRST) st_wt4(ss + (size_t)row * 32 + u.pn * 4 + wc, __float_as_uint(q)); else ss[(size_t)row * 32 + u.pn * 4 + wc] = q; }
;             }
.LBB0_301:
	s_or_b64 exec, exec, s[44:45]
	v_or_b32_e32 v112, 16, v144
	s_waitcnt lgkmcnt(0)
	v_ashrrev_i32_e32 v113, 31, v112
	v_readlane_b32 s68, v234, 3
	v_add_u32_e32 v132, 0xffffe010, v144
	v_lshlrev_b64 v[122:123], 13, v[112:113]
	v_readlane_b32 s69, v234, 4
	v_readlane_b32 s70, v234, 5
	v_readlane_b32 s71, v234, 6
	v_lshlrev_b64 v[120:121], 13, v[132:133]
	v_lshl_add_u64 v[118:119], s[68:69], 0, v[122:123]
	v_lshl_add_u64 v[120:121], s[70:71], 0, v[120:121]
	v_cmp_gt_i32_e32 vcc, s54, v112
	v_lshlrev_b64 v[126:127], 12, v[112:113]
	v_lshl_add_u64 v[122:123], s[84:85], 0, v[122:123]
	v_cndmask_b32_e32 v119, v121, v119, vcc
	v_cndmask_b32_e32 v118, v120, v118, vcc
	v_lshl_add_u64 v[124:125], v[118:119], 0, v[142:143]
	v_mov_b32_e32 v118, v180
	v_mov_b32_e32 v119, v181
	v_mov_b32_e32 v120, v182
	v_mov_b32_e32 v121, v183
	v_lshl_add_u64 v[126:127], s[20:21], 0, v[126:127]
	v_lshl_add_u64 v[122:123], v[122:123], 0, v[142:143]
	v_lshl_add_u64 v[126:127], v[140:141], 1, v[126:127]
	v_lshl_add_u64 v[152:153], v[126:127], 0, 32
	v_readlane_b32 s72, v234, 7
	v_readlane_b32 s73, v234, 8
	v_readlane_b32 s74, v234, 9
	v_readlane_b32 s75, v234, 10
	v_readlane_b32 s76, v234, 11
	v_readlane_b32 s77, v234, 12
	v_readlane_b32 s78, v234, 13
	v_readlane_b32 s79, v234, 14
	v_readlane_b32 s80, v234, 15
	v_readlane_b32 s81, v234, 16
	v_readlane_b32 s82, v234, 17
	v_readlane_b32 s83, v234, 18
	v_pk_add_f32 v[110:111], v[110:111], v[120:121]
	v_pk_add_f32 v[108:109], v[108:109], v[118:119]
	global_store_dwordx4 v[122:123], v[108:111], off
	v_cvt_pk_bf16_f32 v236, v108, v109
	v_cvt_pk_bf16_f32 v237, v110, v111
	s_nop 0
	v_mov_b32_e32 v118, v184
	v_mov_b32_e32 v119, v185
	v_mov_b32_e32 v120, v186
	v_mov_b32_e32 v121, v187
	v_mul_f32_e32 v109, v109, v109
	v_mul_f32_e32 v111, v111, v111
	v_fmac_f32_e32 v109, v108, v108
	v_fmac_f32_e32 v111, v110, v110
	v_add_f32_e32 v108, v109, v111
	v_pk_add_f32 v[106:107], v[106:107], v[120:121]
	v_pk_add_f32 v[104:105], v[104:105], v[118:119]
	global_store_dwordx4 v[122:123], v[104:107], off offset:64
	v_cvt_pk_bf16_f32 v238, v104, v105
	v_cvt_pk_bf16_f32 v239, v106, v107
	s_nop 0
	s_nop 1
	v_permlane32_swap_b32_e32 v236, v238
	v_permlane32_swap_b32_e32 v237, v239
	s_nop 1
	v_permlane16_swap_b32_e32 v236, v238
	v_permlane16_swap_b32_e32 v237, v239
	v_lshl_add_u64 v[242:243], v[152:153], 0, v[240:241]
	s_nop 0
	global_store_dwordx4 v[242:243], v[236:239], off sc1
	s_nop 1
	v_mov_b32_e32 v118, v188
	v_mov_b32_e32 v119, v189
	v_mov_b32_e32 v120, v190
	v_mov_b32_e32 v121, v191
	v_lshl_add_u64 v[152:153], v[126:127], 0, s[28:29]
	v_mul_f32_e32 v105, v105, v105
	v_mul_f32_e32 v107, v107, v107
	v_fmac_f32_e32 v105, v104, v104
	v_fmac_f32_e32 v107, v106, v106
	v_add_f32_e32 v104, v105, v107
	v_add_f32_e32 v104, v108, v104
	v_pk_add_f32 v[102:103], v[102:103], v[120:121]
	v_pk_add_f32 v[100:101], v[100:101], v[118:119]
	global_store_dwordx4 v[122:123], v[100:103], off offset:512
	v_cvt_pk_bf16_f32 v236, v100, v101
	v_cvt_pk_bf16_f32 v237, v102, v103
	s_nop 0
	v_mov_b32_e32 v118, v196
	v_mov_b32_e32 v119, v197
	v_mov_b32_e32 v120, v198
	v_mov_b32_e32 v121, v199
	v_mul_f32_e32 v101, v101, v101
	v_mul_f32_e32 v103, v103, v103
	v_fmac_f32_e32 v101, v100, v100
	v_fmac_f32_e32 v103, v102, v102
	v_add_f32_e32 v100, v101, v103
	v_add_f32_e32 v100, v104, v100
	v_pk_add_f32 v[98:99], v[98:99], v[120:121]
	v_pk_add_f32 v[96:97], v[96:97], v[118:119]
	v_mul_f32_e32 v102, v99, v99
	v_mul_f32_e32 v101, v97, v97
	v_fmac_f32_e32 v101, v96, v96
	v_fmac_f32_e32 v102, v98, v98
	v_add_f32_e32 v101, v101, v102
	v_add_f32_e32 v102, v100, v101
	ds_bpermute_b32 v103, v116, v102
	global_store_dwordx4 v[122:123], v[96:99], off offset:576
	v_cvt_pk_bf16_f32 v238, v96, v97
	v_cvt_pk_bf16_f32 v239, v98, v99
	s_waitcnt lgkmcnt(0)
	s_nop 0
	v_add_f32_e32 v96, v102, v103
	ds_bpermute_b32 v97, v114, v96
	v_lshl_add_u64 v[98:99], v[126:127], 0, s[30:31]
	s_nop 1
	v_permlane32_swap_b32_e32 v236, v238
	v_permlane32_swap_b32_e32 v237, v239
	s_nop 1
	v_permlane16_swap_b32_e32 v236, v238
	v_permlane16_swap_b32_e32 v237, v239
	v_lshl_add_u64 v[242:243], v[98:99], 0, v[240:241]
	s_nop 0
	global_store_dwordx4 v[242:243], v[236:239], off sc1
	s_nop 1
	s_and_saveexec_b64 s[44:45], s[4:5]
	s_cbranch_execz .LBB0_303
	s_waitcnt lgkmcnt(0)
	v_add_f32_e32 v98, v96, v97
	v_lshlrev_b64 v[96:97], 7, v[112:113]
	v_lshl_add_u64 v[96:97], s[2:3], 0, v[96:97]
	v_lshl_add_u64 v[96:97], s[42:43], 2, v[96:97]
	s_lshl_b32 s10, s55, 2
	v_lshl_add_u64 v[96:97], v[96:97], 0, s[10:11]
	global_store_dword v[96:97], v98, off sc1
; __device__ __forceinline__ unsigned cvt_pk_bf16(float lo, float hi) { unsigned r; asm volatile("v_cvt_pk_bf16_f32 %0, %1, %2" : "=v"(r) : "v"(lo), "v"(hi)); return r; }
; __device__ __forceinline__ void st_wt8(void* ptr, u32x2 v) { asm volatile("global_store_dwordx2 %0, %1, off sc1" :: "v"(ptr), "v"(v) : "memory"); }
; __device__ __forceinline__ void st_wt4(void* ptr, unsigned v) { asm volatile("global_store_dword %0, %1, off sc1" :: "v"(ptr), "v"(v) : "memory"); }
;     __device__ __forceinline__ void operator()(const f32x4 (&acc)[2][2][4][2], const pg8::Unit& u, int wr, int wc, int fr, int fq) const {
;     ...
;         for (int ai = 0; ai < 2; ++ai)
; #pragma unroll
;             for (int m = 0; m < 4; ++m) {
;                 const int row = row0 + ai * 128 + m * 16;
;                 float* orow = oy + (size_t)row * DM + col0;
;                 const float* xr = FIRST ? ((row < MP ? xp + (size_t)row * DM : xs + (size_t)(row - MP) * DM) + col0) : orow;
;                 float q = 0.f;
; #pragma unroll
;                 for (int bj = 0; bj < 2; ++bj)
; #pragma unroll
;                     for (int n = 0; n < 2; ++n) {
;                         const f32x4 xv = *(const f32x4*)(xr + bj * 128 + n * 16);
;                         const f32x4 o = xv + acc[ai][bj][m][n];
;                         *(f32x4*)(orow + bj * 128 + n * 16) = o;
;                         q += (o[0] * o[0] + o[1] * o[1]) + (o[2] * o[2] + o[3] * o[3]);
;                         if (FIRST) { u32x2 w; w.x = cvt_pk_bf16(o[0], o[1]); w.y = cvt_pk_bf16(o[2], o[3]); st_wt8(xb + (size_t)row * DM + col0 + bj * 128 + n * 16, w); }
;                     }
;                 q += __shfl_xor(q, 16); q += __shfl_xor(q, 32);
;                 if (fq == 0) { if (FIRST) st_wt4(ss + (size_t)row * 32 + u.pn * 4 + wc, __float_as_uint(q)); else ss[(size_t)row * 32 + u.pn * 4 + wc] = q; }
;             }
.LBB0_303:
	s_or_b64 exec, exec, s[44:45]
	v_or_b32_e32 v96, 32, v144
	s_waitcnt lgkmcnt(0)
	v_ashrrev_i32_e32 v97, 31, v96
	v_readlane_b32 s68, v234, 3
	v_add_u32_e32 v132, 0xffffe020, v144
	v_lshlrev_b64 v[102:103], 13, v[96:97]
	v_readlane_b32 s69, v234, 4
	v_readlane_b32 s70, v234, 5
	v_readlane_b32 s71, v234, 6
	v_lshlrev_b64 v[100:101], 13, v[132:133]
	v_lshl_add_u64 v[98:99], s[68:69], 0, v[102:103]
	v_lshl_add_u64 v[100:101], s[70:71], 0, v[100:101]
	v_cmp_gt_i32_e32 vcc, s54, v96
	v_lshlrev_b64 v[106:107], 12, v[96:97]
	v_lshl_add_u64 v[102:103], s[84:85], 0, v[102:103]
	v_cndmask_b32_e32 v99, v101, v99, vcc
	v_cndmask_b32_e32 v98, v100, v98, vcc
	v_lshl_add_u64 v[104:105], v[98:99], 0, v[142:143]
	v_mov_b32_e32 v98, v200
	v_mov_b32_e32 v99, v201
	v_mov_b32_e32 v100, v202
	v_mov_b32_e32 v101, v203
	v_lshl_add_u64 v[106:107], s[20:21], 0, v[106:107]
	v_lshl_add_u64 v[102:103], v[102:103], 0, v[142:143]
	v_lshl_add_u64 v[106:107], v[140:141], 1, v[106:107]
	v_lshl_add_u64 v[108:109], v[106:107], 0, 32
	v_readlane_b32 s72, v234, 7
	v_readlane_b32 s73, v234, 8
	v_readlane_b32 s74, v234, 9
	v_readlane_b32 s75, v234, 10
	v_readlane_b32 s76, v234, 11
	v_readlane_b32 s77, v234, 12
	v_readlane_b32 s78, v234, 13
	v_readlane_b32 s79, v234, 14
	v_readlane_b32 s80, v234, 15
	v_readlane_b32 s81, v234, 16
	v_readlane_b32 s82, v234, 17
	v_readlane_b32 s83, v234, 18
	v_pk_add_f32 v[94:95], v[94:95], v[100:101]
	v_pk_add_f32 v[92:93], v[92:93], v[98:99]
	global_store_dwordx4 v[102:103], v[92:95], off
	v_cvt_pk_bf16_f32 v236, v92, v93
	v_cvt_pk_bf16_f32 v237, v94, v95
	s_nop 0
	v_mov_b32_e32 v98, v204
	v_mov_b32_e32 v99, v205
	v_mov_b32_e32 v100, v206
	v_mov_b32_e32 v101, v207
	v_mul_f32_e32 v93, v93, v93
	v_mul_f32_e32 v95, v95, v95
	v_fmac_f32_e32 v93, v92, v92
	v_fmac_f32_e32 v95, v94, v94
	v_add_f32_e32 v92, v93, v95
	v_pk_add_f32 v[90:91], v[90:91], v[100:101]
	v_pk_add_f32 v[88:89], v[88:89], v[98:99]
	global_store_dwordx4 v[102:103], v[88:91], off offset:64
	v_cvt_pk_bf16_f32 v238, v88, v89
	v_cvt_pk_bf16_f32 v239, v90, v91
	s_nop 0
	s_nop 1
	v_permlane32_swap_b32_e32 v236, v238
	v_permlane32_swap_b32_e32 v237, v239
	s_nop 1
	v_permlane16_swap_b32_e32 v236, v238
	v_permlane16_swap_b32_e32 v237, v239
	v_lshl_add_u64 v[242:243], v[108:109], 0, v[240:241]
	s_nop 0
	global_store_dwordx4 v[242:243], v[236:239], off sc1
	s_nop 1
	v_mov_b32_e32 v98, v208
	v_mov_b32_e32 v99, v209
	v_mov_b32_e32 v100, v210
	v_mov_b32_e32 v101, v211
	v_lshl_add_u64 v[108:109], v[106:107], 0, s[28:29]
	v_mul_f32_e32 v89, v89, v89
	v_mul_f32_e32 v91, v91, v91
	v_fmac_f32_e32 v89, v88, v88
	v_fmac_f32_e32 v91, v90, v90
	v_add_f32_e32 v88, v89, v91
	v_add_f32_e32 v88, v92, v88
	v_pk_add_f32 v[86:87], v[86:87], v[100:101]
	v_pk_add_f32 v[84:85], v[84:85], v[98:99]
	global_store_dwordx4 v[102:103], v[84:87], off offset:512
	v_cvt_pk_bf16_f32 v236, v84, v85
	v_cvt_pk_bf16_f32 v237, v86, v87
	s_nop 0
	v_mov_b32_e32 v98, v212
	v_mov_b32_e32 v99, v213
	v_mov_b32_e32 v100, v214
	v_mov_b32_e32 v101, v215
	v_mul_f32_e32 v85, v85, v85
	v_mul_f32_e32 v87, v87, v87
	v_fmac_f32_e32 v85, v84, v84
	v_fmac_f32_e32 v87, v86, v86
	v_add_f32_e32 v84, v85, v87
	v_add_f32_e32 v84, v88, v84
	v_pk_add_f32 v[82:83], v[82:83], v[100:101]
	v_pk_add_f32 v[80:81], v[80:81], v[98:99]
	v_mul_f32_e32 v86, v83, v83
	v_mul_f32_e32 v85, v81, v81
	v_fmac_f32_e32 v85, v80, v80
	v_fmac_f32_e32 v86, v82, v82
	v_add_f32_e32 v85, v85, v86
	v_add_f32_e32 v86, v84, v85
	ds_bpermute_b32 v87, v116, v86
	global_store_dwordx4 v[102:103], v[80:83], off offset:576
	v_cvt_pk_bf16_f32 v238, v80, v81
	v_cvt_pk_bf16_f32 v239, v82, v83
	s_waitcnt lgkmcnt(0)
	s_nop 0
	v_add_f32_e32 v80, v86, v87
	ds_bpermute_b32 v81, v114, v80
	v_lshl_add_u64 v[82:83], v[106:107], 0, s[30:31]
	s_nop 1
	v_permlane32_swap_b32_e32 v236, v238
	v_permlane32_swap_b32_e32 v237, v239
	s_nop 1
	v_permlane16_swap_b32_e32 v236, v238
	v_permlane16_swap_b32_e32 v237, v239
	v_lshl_add_u64 v[242:243], v[82:83], 0, v[240:241]
	s_nop 0
	global_store_dwordx4 v[242:243], v[236:239], off sc1
	s_nop 1
	s_and_saveexec_b64 s[44:45], s[4:5]
	s_cbranch_execz .LBB0_305
	s_waitcnt lgkmcnt(0)
	v_add_f32_e32 v82, v80, v81
	v_lshlrev_b64 v[80:81], 7, v[96:97]
	v_lshl_add_u64 v[80:81], s[2:3], 0, v[80:81]
	v_lshl_add_u64 v[80:81], s[42:43], 2, v[80:81]
	s_lshl_b32 s10, s55, 2
	v_lshl_add_u64 v[80:81], v[80:81], 0, s[10:11]
	global_store_dword v[80:81], v82, off sc1
; __device__ __forceinline__ unsigned cvt_pk_bf16(float lo, float hi) { unsigned r; asm volatile("v_cvt_pk_bf16_f32 %0, %1, %2" : "=v"(r) : "v"(lo), "v"(hi)); return r; }
; __device__ __forceinline__ void st_wt8(void* ptr, u32x2 v) { asm volatile("global_store_dwordx2 %0, %1, off sc1" :: "v"(ptr), "v"(v) : "memory"); }
; __device__ __forceinline__ void st_wt4(void* ptr, unsigned v) { asm volatile("global_store_dword %0, %1, off sc1" :: "v"(ptr), "v"(v) : "memory"); }
;     __device__ __forceinline__ void operator()(const f32x4 (&acc)[2][2][4][2], const pg8::Unit& u, int wr, int wc, int fr, int fq) const {
;     ...
;         for (int ai = 0; ai < 2; ++ai)
; #pragma unroll
;             for (int m = 0; m < 4; ++m) {
;                 const int row = row0 + ai * 128 + m * 16;
;                 float* orow = oy + (size_t)row * DM + col0;
;                 const float* xr = FIRST ? ((row < MP ? xp + (size_t)row * DM : xs + (size_t)(row - MP) * DM) + col0) : orow;
;                 float q = 0.f;
; #pragma unroll
;                 for (int bj = 0; bj < 2; ++bj)
; #pragma unroll
;                     for (int n = 0; n < 2; ++n) {
;                         const f32x4 xv = *(const f32x4*)(xr + bj * 128 + n * 16);
;                         const f32x4 o = xv + acc[ai][bj][m][n];
;                         *(f32x4*)(orow + bj * 128 + n * 16) = o;
;                         q += (o[0] * o[0] + o[1] * o[1]) + (o[2] * o[2] + o[3] * o[3]);
;                         if (FIRST) { u32x2 w; w.x = cvt_pk_bf16(o[0], o[1]); w.y = cvt_pk_bf16(o[2], o[3]); st_wt8(xb + (size_t)row * DM + col0 + bj * 128 + n * 16, w); }
;                     }
;                 q += __shfl_xor(q, 16); q += __shfl_xor(q, 32);
;                 if (fq == 0) { if (FIRST) st_wt4(ss + (size_t)row * 32 + u.pn * 4 + wc, __float_as_uint(q)); else ss[(size_t)row * 32 + u.pn * 4 + wc] = q; }
.LBB0_305:
	s_or_b64 exec, exec, s[44:45]
	v_or_b32_e32 v80, 48, v144
	s_waitcnt lgkmcnt(0)
	v_ashrrev_i32_e32 v81, 31, v80
	v_readlane_b32 s68, v234, 3
	v_add_u32_e32 v132, 0xffffe030, v144
	v_lshlrev_b64 v[86:87], 13, v[80:81]
	v_readlane_b32 s69, v234, 4
	v_readlane_b32 s70, v234, 5
	v_readlane_b32 s71, v234, 6
	v_lshlrev_b64 v[84:85], 13, v[132:133]
	v_lshl_add_u64 v[82:83], s[68:69], 0, v[86:87]
	v_lshl_add_u64 v[84:85], s[70:71], 0, v[84:85]
	v_cmp_gt_i32_e32 vcc, s54, v80
	v_lshlrev_b64 v[90:91], 12, v[80:81]
	v_lshl_add_u64 v[86:87], s[84:85], 0, v[86:87]
	v_cndmask_b32_e32 v83, v85, v83, vcc
	v_cndmask_b32_e32 v82, v84, v82, vcc
	v_lshl_add_u64 v[88:89], v[82:83], 0, v[142:143]
	v_mov_b32_e32 v82, v216
	v_mov_b32_e32 v83, v217
	v_mov_b32_e32 v84, v218
	v_mov_b32_e32 v85, v219
	v_lshl_add_u64 v[90:91], s[20:21], 0, v[90:91]
	v_lshl_add_u64 v[86:87], v[86:87], 0, v[142:143]
	v_lshl_add_u64 v[90:91], v[140:141], 1, v[90:91]
	v_lshl_add_u64 v[92:93], v[90:91], 0, 32
	v_readlane_b32 s72, v234, 7
	v_readlane_b32 s73, v234, 8
	v_readlane_b32 s74, v234, 9
	v_readlane_b32 s75, v234, 10
	v_readlane_b32 s76, v234, 11
	v_readlane_b32 s77, v234, 12
	v_readlane_b32 s78, v234, 13
	v_readlane_b32 s79, v234, 14
	v_readlane_b32 s80, v234, 15
	v_readlane_b32 s81, v234, 16
	v_readlane_b32 s82, v234, 17
	v_readlane_b32 s83, v234, 18
	v_pk_add_f32 v[78:79], v[78:79], v[84:85]
	v_pk_add_f32 v[76:77], v[76:77], v[82:83]
	global_store_dwordx4 v[86:87], v[76:79], off
	v_cvt_pk_bf16_f32 v236, v76, v77
	v_cvt_pk_bf16_f32 v237, v78, v79
	s_nop 0
	v_mov_b32_e32 v82, v220
	v_mov_b32_e32 v83, v221
	v_mov_b32_e32 v84, v222
	v_mov_b32_e32 v85, v223
	v_mul_f32_e32 v77, v77, v77
	v_mul_f32_e32 v79, v79, v79
	v_fmac_f32_e32 v77, v76, v76
	v_fmac_f32_e32 v79, v78, v78
	v_add_f32_e32 v76, v77, v79
	v_pk_add_f32 v[74:75], v[74:75], v[84:85]
	v_pk_add_f32 v[72:73], v[72:73], v[82:83]
	global_store_dwordx4 v[86:87], v[72:75], off offset:64
	v_cvt_pk_bf16_f32 v238, v72, v73
	v_cvt_pk_bf16_f32 v239, v74, v75
	s_nop 0
	s_nop 1
	v_permlane32_swap_b32_e32 v236, v238
	v_permlane32_swap_b32_e32 v237, v239
	s_nop 1
	v_permlane16_swap_b32_e32 v236, v238
	v_permlane16_swap_b32_e32 v237, v239
	v_lshl_add_u64 v[242:243], v[92:93], 0, v[240:241]
	s_nop 0
	global_store_dwordx4 v[242:243], v[236:239], off sc1
	s_nop 1
	v_mov_b32_e32 v82, v224
	v_mov_b32_e32 v83, v225
	v_mov_b32_e32 v84, v226
	v_mov_b32_e32 v85, v227
	v_lshl_add_u64 v[92:93], v[90:91], 0, s[28:29]
	v_mul_f32_e32 v73, v73, v73
	v_mul_f32_e32 v75, v75, v75
	v_fmac_f32_e32 v73, v72, v72
	v_fmac_f32_e32 v75, v74, v74
	v_add_f32_e32 v72, v73, v75
	v_add_f32_e32 v72, v76, v72
	v_pk_add_f32 v[70:71], v[70:71], v[84:85]
	v_pk_add_f32 v[68:69], v[68:69], v[82:83]
	global_store_dwordx4 v[86:87], v[68:71], off offset:512
	v_cvt_pk_bf16_f32 v236, v68, v69
	v_cvt_pk_bf16_f32 v237, v70, v71
	s_nop 0
	v_mov_b32_e32 v82, v228
	v_mov_b32_e32 v83, v229
	v_mov_b32_e32 v84, v230
	v_mov_b32_e32 v85, v231
	v_mul_f32_e32 v69, v69, v69
	v_mul_f32_e32 v71, v71, v71
	v_fmac_f32_e32 v69, v68, v68
	v_fmac_f32_e32 v71, v70, v70
	v_add_f32_e32 v68, v69, v71
	v_add_f32_e32 v68, v72, v68
	v_pk_add_f32 v[66:67], v[66:67], v[84:85]
	v_pk_add_f32 v[64:65], v[64:65], v[82:83]
	v_mul_f32_e32 v70, v67, v67
	v_mul_f32_e32 v69, v65, v65
	v_fmac_f32_e32 v69, v64, v64
	v_fmac_f32_e32 v70, v66, v66
	v_add_f32_e32 v69, v69, v70
	v_add_f32_e32 v70, v68, v69
	ds_bpermute_b32 v71, v116, v70
	global_store_dwordx4 v[86:87], v[64:67], off offset:576
	v_cvt_pk_bf16_f32 v238, v64, v65
	v_cvt_pk_bf16_f32 v239, v66, v67
	s_waitcnt lgkmcnt(0)
	s_nop 0
	v_add_f32_e32 v64, v70, v71
	ds_bpermute_b32 v65, v114, v64
	v_lshl_add_u64 v[66:67], v[90:91], 0, s[30:31]
	s_nop 1
	v_permlane32_swap_b32_e32 v236, v238
	v_permlane32_swap_b32_e32 v237, v239
	s_nop 1
	v_permlane16_swap_b32_e32 v236, v238
	v_permlane16_swap_b32_e32 v237, v239
	v_lshl_add_u64 v[242:243], v[66:67], 0, v[240:241]
	s_nop 0
	global_store_dwordx4 v[242:243], v[236:239], off sc1
	s_nop 1
	s_and_saveexec_b64 s[44:45], s[4:5]
	s_cbranch_execz .LBB0_307
	s_waitcnt lgkmcnt(0)
	v_add_f32_e32 v66, v64, v65
	v_lshlrev_b64 v[64:65], 7, v[80:81]
	v_lshl_add_u64 v[64:65], s[2:3], 0, v[64:65]
	v_lshl_add_u64 v[64:65], s[42:43], 2, v[64:65]
	s_lshl_b32 s10, s55, 2
	v_lshl_add_u64 v[64:65], v[64:65], 0, s[10:11]
	global_store_dword v[64:65], v66, off sc1
; __device__ __forceinline__ unsigned cvt_pk_bf16(float lo, float hi) { unsigned r; asm volatile("v_cvt_pk_bf16_f32 %0, %1, %2" : "=v"(r) : "v"(lo), "v"(hi)); return r; }
; __device__ __forceinline__ void st_wt8(void* ptr, u32x2 v) { asm volatile("global_store_dwordx2 %0, %1, off sc1" :: "v"(ptr), "v"(v) : "memory"); }
; __device__ __forceinline__ void st_wt4(void* ptr, unsigned v) { asm volatile("global_store_dword %0, %1, off sc1" :: "v"(ptr), "v"(v) : "memory"); }
;     __device__ __forceinline__ void operator()(const f32x4 (&acc)[2][2][4][2], const pg8::Unit& u, int wr, int wc, int fr, int fq) const {
;     ...
;         for (int ai = 0; ai < 2; ++ai)
; #pragma unroll
;             for (int m = 0; m < 4; ++m) {
;                 const int row = row0 + ai * 128 + m * 16;
;                 float* orow = oy + (size_t)row * DM + col0;
;                 const float* xr = FIRST ? ((row < MP ? xp + (size_t)row * DM : xs + (size_t)(row - MP) * DM) + col0) : orow;
;                 float q = 0.f;
; #pragma unroll
;                 for (int bj = 0; bj < 2; ++bj)
; #pragma unroll
;                     for (int n = 0; n < 2; ++n) {
;                         const f32x4 xv = *(const f32x4*)(xr + bj * 128 + n * 16);
;                         const f32x4 o = xv + acc[ai][bj][m][n];
;                         *(f32x4*)(orow + bj * 128 + n * 16) = o;
;                         q += (o[0] * o[0] + o[1] * o[1]) + (o[2] * o[2] + o[3] * o[3]);
;                         if (FIRST) { u32x2 w; w.x = cvt_pk_bf16(o[0], o[1]); w.y = cvt_pk_bf16(o[2], o[3]); st_wt8(xb + (size_t)row * DM + col0 + bj * 128 + n * 16, w); }
;                     }
;                 q += __shfl_xor(q, 16); q += __shfl_xor(q, 32);
;                 if (fq == 0) { if (FIRST) st_wt4(ss + (size_t)row * 32 + u.pn * 4 + wc, __float_as_uint(q)); else ss[(size_t)row * 32 + u.pn * 4 + wc] = q; }
.LBB0_307:
	s_or_b64 exec, exec, s[44:45]
	v_add_u32_e32 v64, 0x80, v144
	s_waitcnt lgkmcnt(0)
	v_ashrrev_i32_e32 v65, 31, v64
	v_readlane_b32 s68, v234, 3
	v_add_u32_e32 v132, 0xffffe080, v144
	v_lshlrev_b64 v[70:71], 13, v[64:65]
	v_readlane_b32 s69, v234, 4
	v_readlane_b32 s70, v234, 5
	v_readlane_b32 s71, v234, 6
	v_lshlrev_b64 v[68:69], 13, v[132:133]
	s_movk_i32 s9, 0x1f80
	v_lshl_add_u64 v[66:67], s[68:69], 0, v[70:71]
	v_lshl_add_u64 v[68:69], s[70:71], 0, v[68:69]
	v_cmp_gt_i32_e32 vcc, s9, v144
	v_lshlrev_b64 v[74:75], 12, v[64:65]
	v_lshl_add_u64 v[70:71], s[84:85], 0, v[70:71]
	v_cndmask_b32_e32 v67, v69, v67, vcc
	v_cndmask_b32_e32 v66, v68, v66, vcc
	v_lshl_add_u64 v[72:73], v[66:67], 0, v[142:143]
	s_mov_b64 s[98:99], 0x100000
	v_lshl_add_u64 v[192:193], v[232:233], 0, s[98:99]
	global_load_dwordx4 v[164:167], v[192:193], off
	global_load_dwordx4 v[168:171], v[192:193], off offset:64
	global_load_dwordx4 v[172:175], v[192:193], off offset:512
	global_load_dwordx4 v[176:179], v[192:193], off offset:576
	s_mov_b64 s[98:99], 0x120000
	v_lshl_add_u64 v[192:193], v[232:233], 0, s[98:99]
	global_load_dwordx4 v[180:183], v[192:193], off
	global_load_dwordx4 v[184:187], v[192:193], off offset:64
	global_load_dwordx4 v[188:191], v[192:193], off offset:512
	global_load_dwordx4 v[196:199], v[192:193], off offset:576
	s_mov_b64 s[98:99], 0x140000
	v_lshl_add_u64 v[192:193], v[232:233], 0, s[98:99]
	global_load_dwordx4 v[200:203], v[192:193], off
	global_load_dwordx4 v[204:207], v[192:193], off offset:64
	global_load_dwordx4 v[208:211], v[192:193], off offset:512
	global_load_dwordx4 v[212:215], v[192:193], off offset:576
	s_mov_b64 s[98:99], 0x160000
	v_lshl_add_u64 v[192:193], v[232:233], 0, s[98:99]
	global_load_dwordx4 v[216:219], v[192:193], off
	global_load_dwordx4 v[220:223], v[192:193], off offset:64
	global_load_dwordx4 v[224:227], v[192:193], off offset:512
	global_load_dwordx4 v[228:231], v[192:193], off offset:576
	s_waitcnt vmcnt(0)
	v_mov_b32_e32 v66, v164
	v_mov_b32_e32 v67, v165
	v_mov_b32_e32 v68, v166
	v_mov_b32_e32 v69, v167
	v_lshl_add_u64 v[74:75], s[20:21], 0, v[74:75]
	v_lshl_add_u64 v[70:71], v[70:71], 0, v[142:143]
	v_lshl_add_u64 v[74:75], v[140:141], 1, v[74:75]
	v_lshl_add_u64 v[76:77], v[74:75], 0, 32
	v_readlane_b32 s72, v234, 7
	v_readlane_b32 s73, v234, 8
	v_readlane_b32 s74, v234, 9
	v_readlane_b32 s75, v234, 10
	v_readlane_b32 s76, v234, 11
	v_readlane_b32 s77, v234, 12
	v_readlane_b32 s78, v234, 13
	v_readlane_b32 s79, v234, 14
	v_readlane_b32 s80, v234, 15
	v_readlane_b32 s81, v234, 16
	v_readlane_b32 s82, v234, 17
	v_readlane_b32 s83, v234, 18
	v_pk_add_f32 v[62:63], v[62:63], v[68:69]
	v_pk_add_f32 v[60:61], v[60:61], v[66:67]
	global_store_dwordx4 v[70:71], v[60:63], off
	v_cvt_pk_bf16_f32 v236, v60, v61
	v_cvt_pk_bf16_f32 v237, v62, v63
	s_nop 0
	v_mov_b32_e32 v66, v168
	v_mov_b32_e32 v67, v169
	v_mov_b32_e32 v68, v170
	v_mov_b32_e32 v69, v171
	v_mul_f32_e32 v61, v61, v61
	v_mul_f32_e32 v63, v63, v63
	v_fmac_f32_e32 v61, v60, v60
	v_fmac_f32_e32 v63, v62, v62
	v_add_f32_e32 v60, v61, v63
	v_pk_add_f32 v[58:59], v[58:59], v[68:69]
	v_pk_add_f32 v[56:57], v[56:57], v[66:67]
	global_store_dwordx4 v[70:71], v[56:59], off offset:64
	v_cvt_pk_bf16_f32 v238, v56, v57
	v_cvt_pk_bf16_f32 v239, v58, v59
	s_nop 0
	s_nop 1
	v_permlane32_swap_b32_e32 v236, v238
	v_permlane32_swap_b32_e32 v237, v239
	s_nop 1
	v_permlane16_swap_b32_e32 v236, v238
	v_permlane16_swap_b32_e32 v237, v239
	v_lshl_add_u64 v[242:243], v[76:77], 0, v[240:241]
	s_nop 0
	global_store_dwordx4 v[242:243], v[236:239], off sc1
	s_nop 1
	v_mov_b32_e32 v66, v172
	v_mov_b32_e32 v67, v173
	v_mov_b32_e32 v68, v174
	v_mov_b32_e32 v69, v175
	v_lshl_add_u64 v[76:77], v[74:75], 0, s[28:29]
	v_mul_f32_e32 v57, v57, v57
	v_mul_f32_e32 v59, v59, v59
	v_fmac_f32_e32 v57, v56, v56
	v_fmac_f32_e32 v59, v58, v58
	v_add_f32_e32 v56, v57, v59
	v_add_f32_e32 v56, v60, v56
	v_pk_add_f32 v[54:55], v[54:55], v[68:69]
	v_pk_add_f32 v[52:53], v[52:53], v[66:67]
	global_store_dwordx4 v[70:71], v[52:55], off offset:512
	v_cvt_pk_bf16_f32 v236, v52, v53
	v_cvt_pk_bf16_f32 v237, v54, v55
	s_nop 0
	v_mov_b32_e32 v66, v176
	v_mov_b32_e32 v67, v177
	v_mov_b32_e32 v68, v178
	v_mov_b32_e32 v69, v179
	v_mul_f32_e32 v53, v53, v53
	v_mul_f32_e32 v55, v55, v55
	v_fmac_f32_e32 v53, v52, v52
	v_fmac_f32_e32 v55, v54, v54
	v_add_f32_e32 v52, v53, v55
	v_add_f32_e32 v52, v56, v52
	v_pk_add_f32 v[50:51], v[50:51], v[68:69]
	v_pk_add_f32 v[48:49], v[48:49], v[66:67]
	v_mul_f32_e32 v54, v51, v51
	v_mul_f32_e32 v53, v49, v49
	v_fmac_f32_e32 v53, v48, v48
	v_fmac_f32_e32 v54, v50, v50
	v_add_f32_e32 v53, v53, v54
	v_add_f32_e32 v54, v52, v53
	ds_bpermute_b32 v55, v116, v54
	global_store_dwordx4 v[70:71], v[48:51], off offset:576
	v_cvt_pk_bf16_f32 v238, v48, v49
	v_cvt_pk_bf16_f32 v239, v50, v51
	s_waitcnt lgkmcnt(0)
	s_nop 0
	v_add_f32_e32 v48, v54, v55
	ds_bpermute_b32 v49, v114, v48
	v_lshl_add_u64 v[50:51], v[74:75], 0, s[30:31]
	s_nop 1
	v_permlane32_swap_b32_e32 v236, v238
	v_permlane32_swap_b32_e32 v237, v239
	s_nop 1
	v_permlane16_swap_b32_e32 v236, v238
	v_permlane16_swap_b32_e32 v237, v239
	v_lshl_add_u64 v[242:243], v[50:51], 0, v[240:241]
	s_nop 0
	global_store_dwordx4 v[242:243], v[236:239], off sc1
	s_nop 1
	s_and_saveexec_b64 s[44:45], s[4:5]
	s_cbranch_execz .LBB0_309
	s_waitcnt lgkmcnt(0)
	v_add_f32_e32 v50, v48, v49
	v_lshlrev_b64 v[48:49], 7, v[64:65]
	v_lshl_add_u64 v[48:49], s[2:3], 0, v[48:49]
	v_lshl_add_u64 v[48:49], s[42:43], 2, v[48:49]
	s_lshl_b32 s10, s55, 2
	v_lshl_add_u64 v[48:49], v[48:49], 0, s[10:11]
	global_store_dword v[48:49], v50, off sc1
; __device__ __forceinline__ unsigned cvt_pk_bf16(float lo, float hi) { unsigned r; asm volatile("v_cvt_pk_bf16_f32 %0, %1, %2" : "=v"(r) : "v"(lo), "v"(hi)); return r; }
; __device__ __forceinline__ void st_wt8(void* ptr, u32x2 v) { asm volatile("global_store_dwordx2 %0, %1, off sc1" :: "v"(ptr), "v"(v) : "memory"); }
; __device__ __forceinline__ void st_wt4(void* ptr, unsigned v) { asm volatile("global_store_dword %0, %1, off sc1" :: "v"(ptr), "v"(v) : "memory"); }
;     __device__ __forceinline__ void operator()(const f32x4 (&acc)[2][2][4][2], const pg8::Unit& u, int wr, int wc, int fr, int fq) const {
;     ...
;         for (int ai = 0; ai < 2; ++ai)
; #pragma unroll
;             for (int m = 0; m < 4; ++m) {
;                 const int row = row0 + ai * 128 + m * 16;
;                 float* orow = oy + (size_t)row * DM + col0;
;                 const float* xr = FIRST ? ((row < MP ? xp + (size_t)row * DM : xs + (size_t)(row - MP) * DM) + col0) : orow;
;                 float q = 0.f;
; #pragma unroll
;                 for (int bj = 0; bj < 2; ++bj)
; #pragma unroll
;                     for (int n = 0; n < 2; ++n) {
;                         const f32x4 xv = *(const f32x4*)(xr + bj * 128 + n * 16);
;                         const f32x4 o = xv + acc[ai][bj][m][n];
;                         *(f32x4*)(orow + bj * 128 + n * 16) = o;
;                         q += (o[0] * o[0] + o[1] * o[1]) + (o[2] * o[2] + o[3] * o[3]);
;                         if (FIRST) { u32x2 w; w.x = cvt_pk_bf16(o[0], o[1]); w.y = cvt_pk_bf16(o[2], o[3]); st_wt8(xb + (size_t)row * DM + col0 + bj * 128 + n * 16, w); }
;                     }
;                 q += __shfl_xor(q, 16); q += __shfl_xor(q, 32);
;                 if (fq == 0) { if (FIRST) st_wt4(ss + (size_t)row * 32 + u.pn * 4 + wc, __float_as_uint(q)); else ss[(size_t)row * 32 + u.pn * 4 + wc] = q; }
.LBB0_309:
	s_or_b64 exec, exec, s[44:45]
	v_add_u32_e32 v48, 0x90, v144
	s_waitcnt lgkmcnt(0)
	v_ashrrev_i32_e32 v49, 31, v48
	v_readlane_b32 s68, v234, 3
	v_add_u32_e32 v132, 0xffffe090, v144
	v_lshlrev_b64 v[54:55], 13, v[48:49]
	v_readlane_b32 s69, v234, 4
	v_readlane_b32 s70, v234, 5
	v_readlane_b32 s71, v234, 6
	v_lshlrev_b64 v[52:53], 13, v[132:133]
	s_movk_i32 s9, 0x1f70
	v_lshl_add_u64 v[50:51], s[68:69], 0, v[54:55]
	v_lshl_add_u64 v[52:53], s[70:71], 0, v[52:53]
	v_cmp_gt_i32_e32 vcc, s9, v144
	v_lshlrev_b64 v[58:59], 12, v[48:49]
	v_lshl_add_u64 v[54:55], s[84:85], 0, v[54:55]
	v_cndmask_b32_e32 v51, v53, v51, vcc
	v_cndmask_b32_e32 v50, v52, v50, vcc
	v_lshl_add_u64 v[56:57], v[50:51], 0, v[142:143]
	v_mov_b32_e32 v50, v180
	v_mov_b32_e32 v51, v181
	v_mov_b32_e32 v52, v182
	v_mov_b32_e32 v53, v183
	v_lshl_add_u64 v[58:59], s[20:21], 0, v[58:59]
	v_lshl_add_u64 v[54:55], v[54:55], 0, v[142:143]
	v_lshl_add_u64 v[58:59], v[140:141], 1, v[58:59]
	v_lshl_add_u64 v[60:61], v[58:59], 0, 32
	v_readlane_b32 s72, v234, 7
	v_readlane_b32 s73, v234, 8
	v_readlane_b32 s74, v234, 9
	v_readlane_b32 s75, v234, 10
	v_readlane_b32 s76, v234, 11
	v_readlane_b32 s77, v234, 12
	v_readlane_b32 s78, v234, 13
	v_readlane_b32 s79, v234, 14
	v_readlane_b32 s80, v234, 15
	v_readlane_b32 s81, v234, 16
	v_readlane_b32 s82, v234, 17
	v_readlane_b32 s83, v234, 18
	v_pk_add_f32 v[46:47], v[46:47], v[52:53]
	v_pk_add_f32 v[44:45], v[44:45], v[50:51]
	global_store_dwordx4 v[54:55], v[44:47], off
	v_cvt_pk_bf16_f32 v236, v44, v45
	v_cvt_pk_bf16_f32 v237, v46, v47
	s_nop 0
	v_mov_b32_e32 v50, v184
	v_mov_b32_e32 v51, v185
	v_mov_b32_e32 v52, v186
	v_mov_b32_e32 v53, v187
	v_mul_f32_e32 v45, v45, v45
	v_mul_f32_e32 v47, v47, v47
	v_fmac_f32_e32 v45, v44, v44
	v_fmac_f32_e32 v47, v46, v46
	v_add_f32_e32 v44, v45, v47
	v_pk_add_f32 v[42:43], v[42:43], v[52:53]
	v_pk_add_f32 v[40:41], v[40:41], v[50:51]
	global_store_dwordx4 v[54:55], v[40:43], off offset:64
	v_cvt_pk_bf16_f32 v238, v40, v41
	v_cvt_pk_bf16_f32 v239, v42, v43
	s_nop 0
	s_nop 1
	v_permlane32_swap_b32_e32 v236, v238
	v_permlane32_swap_b32_e32 v237, v239
	s_nop 1
	v_permlane16_swap_b32_e32 v236, v238
	v_permlane16_swap_b32_e32 v237, v239
	v_lshl_add_u64 v[242:243], v[60:61], 0, v[240:241]
	s_nop 0
	global_store_dwordx4 v[242:243], v[236:239], off sc1
	s_nop 1
	v_mov_b32_e32 v50, v188
	v_mov_b32_e32 v51, v189
	v_mov_b32_e32 v52, v190
	v_mov_b32_e32 v53, v191
	v_lshl_add_u64 v[60:61], v[58:59], 0, s[28:29]
	v_mul_f32_e32 v41, v41, v41
	v_mul_f32_e32 v43, v43, v43
	v_fmac_f32_e32 v41, v40, v40
	v_fmac_f32_e32 v43, v42, v42
	v_add_f32_e32 v40, v41, v43
	v_add_f32_e32 v40, v44, v40
	v_pk_add_f32 v[38:39], v[38:39], v[52:53]
	v_pk_add_f32 v[36:37], v[36:37], v[50:51]
	global_store_dwordx4 v[54:55], v[36:39], off offset:512
	v_cvt_pk_bf16_f32 v236, v36, v37
	v_cvt_pk_bf16_f32 v237, v38, v39
	s_nop 0
	v_mov_b32_e32 v50, v196
	v_mov_b32_e32 v51, v197
	v_mov_b32_e32 v52, v198
	v_mov_b32_e32 v53, v199
	v_mul_f32_e32 v37, v37, v37
	v_mul_f32_e32 v39, v39, v39
	v_fmac_f32_e32 v37, v36, v36
	v_fmac_f32_e32 v39, v38, v38
	v_add_f32_e32 v36, v37, v39
	v_add_f32_e32 v36, v40, v36
	v_pk_add_f32 v[34:35], v[34:35], v[52:53]
	v_pk_add_f32 v[32:33], v[32:33], v[50:51]
	v_mul_f32_e32 v38, v35, v35
	v_mul_f32_e32 v37, v33, v33
	v_fmac_f32_e32 v37, v32, v32
	v_fmac_f32_e32 v38, v34, v34
	v_add_f32_e32 v37, v37, v38
	v_add_f32_e32 v38, v36, v37
	ds_bpermute_b32 v39, v116, v38
	global_store_dwordx4 v[54:55], v[32:35], off offset:576
	v_cvt_pk_bf16_f32 v238, v32, v33
	v_cvt_pk_bf16_f32 v239, v34, v35
	s_waitcnt lgkmcnt(0)
	s_nop 0
	v_add_f32_e32 v32, v38, v39
	ds_bpermute_b32 v33, v114, v32
	v_lshl_add_u64 v[34:35], v[58:59], 0, s[30:31]
	s_nop 1
	v_permlane32_swap_b32_e32 v236, v238
	v_permlane32_swap_b32_e32 v237, v239
	s_nop 1
	v_permlane16_swap_b32_e32 v236, v238
	v_permlane16_swap_b32_e32 v237, v239
	v_lshl_add_u64 v[242:243], v[34:35], 0, v[240:241]
	s_nop 0
	global_store_dwordx4 v[242:243], v[236:239], off sc1
	s_nop 1
	s_and_saveexec_b64 s[44:45], s[4:5]
	s_cbranch_execz .LBB0_311
	s_waitcnt lgkmcnt(0)
	v_add_f32_e32 v34, v32, v33
	v_lshlrev_b64 v[32:33], 7, v[48:49]
	v_lshl_add_u64 v[32:33], s[2:3], 0, v[32:33]
	v_lshl_add_u64 v[32:33], s[42:43], 2, v[32:33]
	s_lshl_b32 s10, s55, 2
	v_lshl_add_u64 v[32:33], v[32:33], 0, s[10:11]
	global_store_dword v[32:33], v34, off sc1
; __device__ __forceinline__ unsigned cvt_pk_bf16(float lo, float hi) { unsigned r; asm volatile("v_cvt_pk_bf16_f32 %0, %1, %2" : "=v"(r) : "v"(lo), "v"(hi)); return r; }
; __device__ __forceinline__ void st_wt8(void* ptr, u32x2 v) { asm volatile("global_store_dwordx2 %0, %1, off sc1" :: "v"(ptr), "v"(v) : "memory"); }
; __device__ __forceinline__ void st_wt4(void* ptr, unsigned v) { asm volatile("global_store_dword %0, %1, off sc1" :: "v"(ptr), "v"(v) : "memory"); }
;     __device__ __forceinline__ void operator()(const f32x4 (&acc)[2][2][4][2], const pg8::Unit& u, int wr, int wc, int fr, int fq) const {
;     ...
;         for (int ai = 0; ai < 2; ++ai)
; #pragma unroll
;             for (int m = 0; m < 4; ++m) {
;                 const int row = row0 + ai * 128 + m * 16;
;                 float* orow = oy + (size_t)row * DM + col0;
;                 const float* xr = FIRST ? ((row < MP ? xp + (size_t)row * DM : xs + (size_t)(row - MP) * DM) + col0) : orow;
;                 float q = 0.f;
; #pragma unroll
;                 for (int bj = 0; bj < 2; ++bj)
; #pragma unroll
;                     for (int n = 0; n < 2; ++n) {
;                         const f32x4 xv = *(const f32x4*)(xr + bj * 128 + n * 16);
;                         const f32x4 o = xv + acc[ai][bj][m][n];
;                         *(f32x4*)(orow + bj * 128 + n * 16) = o;
;                         q += (o[0] * o[0] + o[1] * o[1]) + (o[2] * o[2] + o[3] * o[3]);
;                         if (FIRST) { u32x2 w; w.x = cvt_pk_bf16(o[0], o[1]); w.y = cvt_pk_bf16(o[2], o[3]); st_wt8(xb + (size_t)row * DM + col0 + bj * 128 + n * 16, w); }
;                     }
;                 q += __shfl_xor(q, 16); q += __shfl_xor(q, 32);
;                 if (fq == 0) { if (FIRST) st_wt4(ss + (size_t)row * 32 + u.pn * 4 + wc, __float_as_uint(q)); else ss[(size_t)row * 32 + u.pn * 4 + wc] = q; }
.LBB0_311:
	s_or_b64 exec, exec, s[44:45]
	v_add_u32_e32 v32, 0xa0, v144
	s_waitcnt lgkmcnt(0)
	v_ashrrev_i32_e32 v33, 31, v32
	v_readlane_b32 s68, v234, 3
	v_add_u32_e32 v132, 0xffffe0a0, v144
	v_lshlrev_b64 v[38:39], 13, v[32:33]
	v_readlane_b32 s69, v234, 4
	v_readlane_b32 s70, v234, 5
	v_readlane_b32 s71, v234, 6
	v_lshlrev_b64 v[36:37], 13, v[132:133]
	s_movk_i32 s9, 0x1f60
	v_lshl_add_u64 v[34:35], s[68:69], 0, v[38:39]
	v_lshl_add_u64 v[36:37], s[70:71], 0, v[36:37]
	v_cmp_gt_i32_e32 vcc, s9, v144
	v_lshlrev_b64 v[42:43], 12, v[32:33]
	v_lshl_add_u64 v[38:39], s[84:85], 0, v[38:39]
	v_cndmask_b32_e32 v35, v37, v35, vcc
	v_cndmask_b32_e32 v34, v36, v34, vcc
	v_lshl_add_u64 v[40:41], v[34:35], 0, v[142:143]
	v_mov_b32_e32 v34, v200
	v_mov_b32_e32 v35, v201
	v_mov_b32_e32 v36, v202
	v_mov_b32_e32 v37, v203
	v_lshl_add_u64 v[42:43], s[20:21], 0, v[42:43]
	v_lshl_add_u64 v[38:39], v[38:39], 0, v[142:143]
	v_lshl_add_u64 v[42:43], v[140:141], 1, v[42:43]
	v_lshl_add_u64 v[44:45], v[42:43], 0, 32
	v_readlane_b32 s72, v234, 7
	v_readlane_b32 s73, v234, 8
	v_readlane_b32 s74, v234, 9
	v_readlane_b32 s75, v234, 10
	v_readlane_b32 s76, v234, 11
	v_readlane_b32 s77, v234, 12
	v_readlane_b32 s78, v234, 13
	v_readlane_b32 s79, v234, 14
	v_readlane_b32 s80, v234, 15
	v_readlane_b32 s81, v234, 16
	v_readlane_b32 s82, v234, 17
	v_readlane_b32 s83, v234, 18
	v_pk_add_f32 v[30:31], v[30:31], v[36:37]
	v_pk_add_f32 v[28:29], v[28:29], v[34:35]
	global_store_dwordx4 v[38:39], v[28:31], off
	v_cvt_pk_bf16_f32 v236, v28, v29
	v_cvt_pk_bf16_f32 v237, v30, v31
	s_nop 0
	v_mov_b32_e32 v34, v204
	v_mov_b32_e32 v35, v205
	v_mov_b32_e32 v36, v206
	v_mov_b32_e32 v37, v207
	v_mul_f32_e32 v29, v29, v29
	v_mul_f32_e32 v31, v31, v31
	v_fmac_f32_e32 v29, v28, v28
	v_fmac_f32_e32 v31, v30, v30
	v_add_f32_e32 v28, v29, v31
	v_pk_add_f32 v[26:27], v[26:27], v[36:37]
	v_pk_add_f32 v[24:25], v[24:25], v[34:35]
	global_store_dwordx4 v[38:39], v[24:27], off offset:64
	v_cvt_pk_bf16_f32 v238, v24, v25
	v_cvt_pk_bf16_f32 v239, v26, v27
	s_nop 0
	s_nop 1
	v_permlane32_swap_b32_e32 v236, v238
	v_permlane32_swap_b32_e32 v237, v239
	s_nop 1
	v_permlane16_swap_b32_e32 v236, v238
	v_permlane16_swap_b32_e32 v237, v239
	v_lshl_add_u64 v[242:243], v[44:45], 0, v[240:241]
	s_nop 0
	global_store_dwordx4 v[242:243], v[236:239], off sc1
	s_nop 1
	v_mov_b32_e32 v34, v208
	v_mov_b32_e32 v35, v209
	v_mov_b32_e32 v36, v210
	v_mov_b32_e32 v37, v211
	v_lshl_add_u64 v[44:45], v[42:43], 0, s[28:29]
	v_mul_f32_e32 v25, v25, v25
	v_mul_f32_e32 v27, v27, v27
	v_fmac_f32_e32 v25, v24, v24
	v_fmac_f32_e32 v27, v26, v26
	v_add_f32_e32 v24, v25, v27
	v_add_f32_e32 v24, v28, v24
	v_pk_add_f32 v[22:23], v[22:23], v[36:37]
	v_pk_add_f32 v[20:21], v[20:21], v[34:35]
	global_store_dwordx4 v[38:39], v[20:23], off offset:512
	v_cvt_pk_bf16_f32 v236, v20, v21
	v_cvt_pk_bf16_f32 v237, v22, v23
	s_nop 0
	v_mov_b32_e32 v34, v212
	v_mov_b32_e32 v35, v213
	v_mov_b32_e32 v36, v214
	v_mov_b32_e32 v37, v215
	v_mul_f32_e32 v21, v21, v21
	v_mul_f32_e32 v23, v23, v23
	v_fmac_f32_e32 v21, v20, v20
	v_fmac_f32_e32 v23, v22, v22
	v_add_f32_e32 v20, v21, v23
	v_add_f32_e32 v20, v24, v20
	v_pk_add_f32 v[18:19], v[18:19], v[36:37]
	v_pk_add_f32 v[16:17], v[16:17], v[34:35]
	v_mul_f32_e32 v22, v19, v19
	v_mul_f32_e32 v21, v17, v17
	v_fmac_f32_e32 v21, v16, v16
	v_fmac_f32_e32 v22, v18, v18
	v_add_f32_e32 v21, v21, v22
	v_add_f32_e32 v22, v20, v21
	ds_bpermute_b32 v23, v116, v22
	global_store_dwordx4 v[38:39], v[16:19], off offset:576
	v_cvt_pk_bf16_f32 v238, v16, v17
	v_cvt_pk_bf16_f32 v239, v18, v19
	s_waitcnt lgkmcnt(0)
	s_nop 0
	v_add_f32_e32 v16, v22, v23
	ds_bpermute_b32 v17, v114, v16
	v_lshl_add_u64 v[18:19], v[42:43], 0, s[30:31]
	s_nop 1
	v_permlane32_swap_b32_e32 v236, v238
	v_permlane32_swap_b32_e32 v237, v239
	s_nop 1
	v_permlane16_swap_b32_e32 v236, v238
	v_permlane16_swap_b32_e32 v237, v239
	v_lshl_add_u64 v[242:243], v[18:19], 0, v[240:241]
	s_nop 0
	global_store_dwordx4 v[242:243], v[236:239], off sc1
	s_nop 1
	s_and_saveexec_b64 s[44:45], s[4:5]
	s_cbranch_execz .LBB0_313
	s_waitcnt lgkmcnt(0)
	v_add_f32_e32 v18, v16, v17
	v_lshlrev_b64 v[16:17], 7, v[32:33]
	v_lshl_add_u64 v[16:17], s[2:3], 0, v[16:17]
	v_lshl_add_u64 v[16:17], s[42:43], 2, v[16:17]
	s_lshl_b32 s10, s55, 2
	v_lshl_add_u64 v[16:17], v[16:17], 0, s[10:11]
	global_store_dword v[16:17], v18, off sc1
; __device__ __forceinline__ unsigned cvt_pk_bf16(float lo, float hi) { unsigned r; asm volatile("v_cvt_pk_bf16_f32 %0, %1, %2" : "=v"(r) : "v"(lo), "v"(hi)); return r; }
; __device__ __forceinline__ void st_wt8(void* ptr, u32x2 v) { asm volatile("global_store_dwordx2 %0, %1, off sc1" :: "v"(ptr), "v"(v) : "memory"); }
; __device__ __forceinline__ void st_wt4(void* ptr, unsigned v) { asm volatile("global_store_dword %0, %1, off sc1" :: "v"(ptr), "v"(v) : "memory"); }
;     __device__ __forceinline__ void operator()(const f32x4 (&acc)[2][2][4][2], const pg8::Unit& u, int wr, int wc, int fr, int fq) const {
;     ...
;         for (int ai = 0; ai < 2; ++ai)
; #pragma unroll
;             for (int m = 0; m < 4; ++m) {
;                 const int row = row0 + ai * 128 + m * 16;
;                 float* orow = oy + (size_t)row * DM + col0;
;                 const float* xr = FIRST ? ((row < MP ? xp + (size_t)row * DM : xs + (size_t)(row - MP) * DM) + col0) : orow;
;                 float q = 0.f;
; #pragma unroll
;                 for (int bj = 0; bj < 2; ++bj)
; #pragma unroll
;                     for (int n = 0; n < 2; ++n) {
;                         const f32x4 xv = *(const f32x4*)(xr + bj * 128 + n * 16);
;                         const f32x4 o = xv + acc[ai][bj][m][n];
;                         *(f32x4*)(orow + bj * 128 + n * 16) = o;
;                         q += (o[0] * o[0] + o[1] * o[1]) + (o[2] * o[2] + o[3] * o[3]);
;                         if (FIRST) { u32x2 w; w.x = cvt_pk_bf16(o[0], o[1]); w.y = cvt_pk_bf16(o[2], o[3]); st_wt8(xb + (size_t)row * DM + col0 + bj * 128 + n * 16, w); }
;                     }
;                 q += __shfl_xor(q, 16); q += __shfl_xor(q, 32);
;                 if (fq == 0) { if (FIRST) st_wt4(ss + (size_t)row * 32 + u.pn * 4 + wc, __float_as_uint(q)); else ss[(size_t)row * 32 + u.pn * 4 + wc] = q; }
.LBB0_313:
	s_or_b64 exec, exec, s[44:45]
	v_add_u32_e32 v16, 0xb0, v144
	s_waitcnt lgkmcnt(0)
	v_ashrrev_i32_e32 v17, 31, v16
	v_readlane_b32 s68, v234, 3
	v_add_u32_e32 v132, 0xffffe0b0, v144
	v_lshlrev_b64 v[22:23], 13, v[16:17]
	v_readlane_b32 s69, v234, 4
	v_readlane_b32 s70, v234, 5
	v_readlane_b32 s71, v234, 6
	v_lshlrev_b64 v[20:21], 13, v[132:133]
	s_movk_i32 s9, 0x1f50
	v_lshl_add_u64 v[18:19], s[68:69], 0, v[22:23]
	v_lshl_add_u64 v[20:21], s[70:71], 0, v[20:21]
	v_cmp_gt_i32_e32 vcc, s9, v144
	v_lshlrev_b64 v[26:27], 12, v[16:17]
	v_lshl_add_u64 v[22:23], s[84:85], 0, v[22:23]
	v_cndmask_b32_e32 v19, v21, v19, vcc
	v_cndmask_b32_e32 v18, v20, v18, vcc
	v_lshl_add_u64 v[24:25], v[18:19], 0, v[142:143]
	v_mov_b32_e32 v18, v216
	v_mov_b32_e32 v19, v217
	v_mov_b32_e32 v20, v218
	v_mov_b32_e32 v21, v219
	v_lshl_add_u64 v[26:27], s[20:21], 0, v[26:27]
	v_lshl_add_u64 v[22:23], v[22:23], 0, v[142:143]
	v_lshl_add_u64 v[26:27], v[140:141], 1, v[26:27]
	v_lshl_add_u64 v[28:29], v[26:27], 0, 32
	v_readlane_b32 s72, v234, 7
	v_readlane_b32 s73, v234, 8
	v_readlane_b32 s74, v234, 9
	v_readlane_b32 s75, v234, 10
	v_readlane_b32 s76, v234, 11
	v_readlane_b32 s77, v234, 12
	v_readlane_b32 s78, v234, 13
	v_readlane_b32 s79, v234, 14
	v_readlane_b32 s80, v234, 15
	v_readlane_b32 s81, v234, 16
	v_readlane_b32 s82, v234, 17
	v_readlane_b32 s83, v234, 18
	v_pk_add_f32 v[14:15], v[14:15], v[20:21]
	v_pk_add_f32 v[12:13], v[12:13], v[18:19]
	global_store_dwordx4 v[22:23], v[12:15], off
	v_cvt_pk_bf16_f32 v236, v12, v13
	v_cvt_pk_bf16_f32 v237, v14, v15
	s_nop 0
	v_mov_b32_e32 v18, v220
	v_mov_b32_e32 v19, v221
	v_mov_b32_e32 v20, v222
	v_mov_b32_e32 v21, v223
	v_mul_f32_e32 v13, v13, v13
	v_mul_f32_e32 v15, v15, v15
	v_fmac_f32_e32 v13, v12, v12
	v_fmac_f32_e32 v15, v14, v14
	v_add_f32_e32 v12, v13, v15
	v_pk_add_f32 v[10:11], v[10:11], v[20:21]
	v_pk_add_f32 v[8:9], v[8:9], v[18:19]
	global_store_dwordx4 v[22:23], v[8:11], off offset:64
	v_cvt_pk_bf16_f32 v238, v8, v9
	v_cvt_pk_bf16_f32 v239, v10, v11
	s_nop 0
	s_nop 1
	v_permlane32_swap_b32_e32 v236, v238
	v_permlane32_swap_b32_e32 v237, v239
	s_nop 1
	v_permlane16_swap_b32_e32 v236, v238
	v_permlane16_swap_b32_e32 v237, v239
	v_lshl_add_u64 v[242:243], v[28:29], 0, v[240:241]
	s_nop 0
	global_store_dwordx4 v[242:243], v[236:239], off sc1
	s_nop 1
	v_mov_b32_e32 v18, v224
	v_mov_b32_e32 v19, v225
	v_mov_b32_e32 v20, v226
	v_mov_b32_e32 v21, v227
	v_lshl_add_u64 v[28:29], v[26:27], 0, s[28:29]
	v_mul_f32_e32 v9, v9, v9
	v_mul_f32_e32 v11, v11, v11
	v_fmac_f32_e32 v9, v8, v8
	v_fmac_f32_e32 v11, v10, v10
	v_add_f32_e32 v8, v9, v11
	v_add_f32_e32 v8, v12, v8
	v_pk_add_f32 v[6:7], v[6:7], v[20:21]
	v_pk_add_f32 v[4:5], v[4:5], v[18:19]
	global_store_dwordx4 v[22:23], v[4:7], off offset:512
	v_cvt_pk_bf16_f32 v236, v4, v5
	v_cvt_pk_bf16_f32 v237, v6, v7
	s_nop 0
	v_mov_b32_e32 v18, v228
	v_mov_b32_e32 v19, v229
	v_mov_b32_e32 v20, v230
	v_mov_b32_e32 v21, v231
	v_mul_f32_e32 v5, v5, v5
	v_mul_f32_e32 v7, v7, v7
	v_fmac_f32_e32 v5, v4, v4
	v_fmac_f32_e32 v7, v6, v6
	v_add_f32_e32 v4, v5, v7
	v_add_f32_e32 v4, v8, v4
	v_pk_add_f32 v[2:3], v[2:3], v[20:21]
	v_pk_add_f32 v[0:1], v[0:1], v[18:19]
	v_mul_f32_e32 v6, v3, v3
	v_mul_f32_e32 v5, v1, v1
	v_fmac_f32_e32 v5, v0, v0
	v_fmac_f32_e32 v6, v2, v2
	v_add_f32_e32 v5, v5, v6
	v_add_f32_e32 v6, v4, v5
	ds_bpermute_b32 v7, v116, v6
	global_store_dwordx4 v[22:23], v[0:3], off offset:576
	v_cvt_pk_bf16_f32 v238, v0, v1
	v_cvt_pk_bf16_f32 v239, v2, v3
	s_waitcnt lgkmcnt(0)
	s_nop 0
	v_add_f32_e32 v0, v6, v7
	ds_bpermute_b32 v1, v114, v0
	v_lshl_add_u64 v[2:3], v[26:27], 0, s[30:31]
	s_nop 1
	v_permlane32_swap_b32_e32 v236, v238
	v_permlane32_swap_b32_e32 v237, v239
	s_nop 1
	v_permlane16_swap_b32_e32 v236, v238
	v_permlane16_swap_b32_e32 v237, v239
	v_lshl_add_u64 v[242:243], v[2:3], 0, v[240:241]
	s_nop 0
	global_store_dwordx4 v[242:243], v[236:239], off sc1
	s_nop 1
	s_and_saveexec_b64 s[44:45], s[4:5]
	s_cbranch_execnz .LBB0_316
	s_or_b64 exec, exec, s[44:45]
	s_andn2_b64 vcc, exec, s[36:37]
	s_mov_b64 s[36:37], -1
	s_cbranch_vccz .LBB0_317

; __device__ __forceinline__ unsigned cvt_pk_bf16(float lo, float hi) { unsigned r; asm volatile("v_cvt_pk_bf16_f32 %0, %1, %2" : "=v"(r) : "v"(lo), "v"(hi)); return r; }
; __device__ __forceinline__ void st_wt8(void* ptr, u32x2 v) { asm volatile("global_store_dwordx2 %0, %1, off sc1" :: "v"(ptr), "v"(v) : "memory"); }
; __device__ __forceinline__ float bf_lo(unsigned w) { return __uint_as_float(w << 16); }
; __device__ __forceinline__ float bf_hi(unsigned w) { return __uint_as_float(w & 0xffff0000u); }
; __device__ __forceinline__ void attn_phase(const Params& p, LAS unsigned char* lds, int cidx) {
;     ...
;         if (active) {
; #pragma unroll
;             for (int mt = 0; mt < 2; ++mt)
; #pragma unroll
;                 for (int dt = 0; dt < 8; ++dt) {
;                     const size_t off = (size_t)(qrow0 + 16 * mt + fr) * DM + h * 128 + 16 * dt + 4 * fq;
;                     const u32x2 zr = __builtin_nontemporal_load((const u32x2*)(sz1 + off)); const f32x4 a = o[mt][dt];
;                     u32x2 w; w.x = cvt_pk_bf16(a[0] * bf_lo(zr.x), a[1] * bf_hi(zr.x)); w.y = cvt_pk_bf16(a[2] * bf_lo(zr.y), a[3] * bf_hi(zr.y));
;                     st_wt8(y1 + off, w);
;                 }
.LBB0_683:
	s_or_b64 exec, exec, s[2:3]
	v_readlane_b32 s2, v234, 58
	v_readlane_b32 s3, v234, 59
	s_andn2_b64 vcc, exec, s[2:3]
	s_cbranch_vccnz .LBB0_685
	v_mbcnt_lo_u32_b32 v240, -1, 0
	v_mbcnt_hi_u32_b32 v240, -1, v240
	v_lshrrev_b32_e32 v240, 4, v240
	v_lshlrev_b32_e32 v240, 3, v240
	v_add_u32_e32 v240, 0xffffffe0, v240
	v_mov_b32_e32 v241, -1
	v_or_b32_e32 v1, s15, v199
	v_lshlrev_b32_e32 v1, 1, v1
	v_or_b32_e32 v176, v176, v1
	v_lshl_add_u64 v[34:35], s[92:93], 0, v[176:177]
	v_readlane_b32 s2, v234, 25
	v_mov_b32_e32 v37, v177
	v_readlane_b32 s3, v234, 26
	v_or_b32_e32 v36, 32, v176
	v_lshl_add_u64 v[36:37], s[92:93], 0, v[36:37]
	v_lshl_add_u64 v[38:39], s[2:3], 0, v[176:177]
	s_mov_b64 s[6:7], 0x60
	s_mov_b64 s[14:15], 0x80
	s_mov_b64 s[18:19], 0xa0
	s_mov_b64 s[20:21], 0xc0
	v_or_b32_e32 v174, v174, v1
	v_lshl_add_u64 v[190:191], s[92:93], 0, v[176:177]
	v_lshl_add_u64 v[188:189], s[92:93], 0, v[174:175]
	global_load_dwordx2 v[204:205], v[190:191], off nt
	global_load_dwordx2 v[206:207], v[190:191], off offset:32 nt
	global_load_dwordx2 v[208:209], v[190:191], off offset:64 nt
	global_load_dwordx2 v[210:211], v[190:191], off offset:96 nt
	global_load_dwordx2 v[212:213], v[190:191], off offset:128 nt
	global_load_dwordx2 v[214:215], v[190:191], off offset:160 nt
	global_load_dwordx2 v[216:217], v[190:191], off offset:192 nt
	global_load_dwordx2 v[218:219], v[190:191], off offset:224 nt
	global_load_dwordx2 v[220:221], v[188:189], off nt
	global_load_dwordx2 v[222:223], v[188:189], off offset:32 nt
	global_load_dwordx2 v[224:225], v[188:189], off offset:64 nt
	global_load_dwordx2 v[226:227], v[188:189], off offset:96 nt
	global_load_dwordx2 v[228:229], v[188:189], off offset:128 nt
	global_load_dwordx2 v[230:231], v[188:189], off offset:160 nt
	global_load_dwordx2 v[232:233], v[188:189], off offset:192 nt
	global_load_dwordx2 v[192:193], v[188:189], off offset:224 nt
	s_mov_b64 s[22:23], 0xe0
	s_waitcnt vmcnt(0)
	v_mov_b32_e32 v34, v204
	v_mov_b32_e32 v35, v205
	v_lshlrev_b32_e32 v40, 16, v34
	v_and_b32_e32 v34, 0xffff0000, v34
	v_lshlrev_b32_e32 v41, 16, v35
	v_and_b32_e32 v35, 0xffff0000, v35
	v_mul_f32_e32 v34, v159, v34
	v_mul_f32_e32 v35, v161, v35
	v_mul_f32_e32 v40, v158, v40
	v_mul_f32_e32 v41, v160, v41
	v_cvt_pk_bf16_f32 v236, v40, v34
	v_cvt_pk_bf16_f32 v237, v41, v35
	v_lshl_add_u64 v[40:41], v[38:39], 0, 32
	v_mov_b32_e32 v34, v206
	v_mov_b32_e32 v35, v207
	v_mov_b32_e32 v37, v177
	v_or_b32_e32 v36, 64, v176
	v_lshl_add_u64 v[36:37], s[92:93], 0, v[36:37]
	v_lshlrev_b32_e32 v42, 16, v34
	v_and_b32_e32 v34, 0xffff0000, v34
	v_lshlrev_b32_e32 v43, 16, v35
	v_and_b32_e32 v35, 0xffff0000, v35
	v_mul_f32_e32 v34, v155, v34
	v_mul_f32_e32 v35, v157, v35
	v_mul_f32_e32 v42, v154, v42
	v_mul_f32_e32 v43, v156, v43
	v_cvt_pk_bf16_f32 v238, v42, v34
	v_cvt_pk_bf16_f32 v239, v43, v35
	s_nop 0
	s_nop 1
	v_permlane32_swap_b32_e32 v236, v238
	v_permlane32_swap_b32_e32 v237, v239
	s_nop 1
	v_permlane16_swap_b32_e32 v236, v238
	v_permlane16_swap_b32_e32 v237, v239
	v_lshl_add_u64 v[242:243], v[40:41], 0, v[240:241]
	s_nop 0
	global_store_dwordx4 v[242:243], v[236:239], off sc1
	s_nop 1
	v_mov_b32_e32 v34, v208
	v_mov_b32_e32 v35, v209
	v_mov_b32_e32 v37, v177
	v_or_b32_e32 v36, 0x60, v176
	v_lshl_add_u64 v[40:41], v[38:39], 0, 64
	v_lshl_add_u64 v[36:37], s[92:93], 0, v[36:37]
	v_lshlrev_b32_e32 v42, 16, v34
	v_and_b32_e32 v34, 0xffff0000, v34
	v_lshlrev_b32_e32 v43, 16, v35
	v_and_b32_e32 v35, 0xffff0000, v35
	v_mul_f32_e32 v34, v151, v34
	v_mul_f32_e32 v35, v153, v35
	v_mul_f32_e32 v42, v150, v42
	v_mul_f32_e32 v43, v152, v43
	v_cvt_pk_bf16_f32 v236, v42, v34
	v_cvt_pk_bf16_f32 v237, v43, v35
	s_nop 0
	v_mov_b32_e32 v34, v210
	v_mov_b32_e32 v35, v211
	v_mov_b32_e32 v37, v177
	v_or_b32_e32 v36, 0x80, v176
	v_lshl_add_u64 v[40:41], v[38:39], 0, s[6:7]
	v_lshl_add_u64 v[36:37], s[92:93], 0, v[36:37]
	v_lshlrev_b32_e32 v42, 16, v34
	v_and_b32_e32 v34, 0xffff0000, v34
	v_lshlrev_b32_e32 v43, 16, v35
	v_and_b32_e32 v35, 0xffff0000, v35
	v_mul_f32_e32 v34, v147, v34
	v_mul_f32_e32 v35, v149, v35
	v_mul_f32_e32 v42, v146, v42
	v_mul_f32_e32 v43, v148, v43
	v_cvt_pk_bf16_f32 v238, v42, v34
	v_cvt_pk_bf16_f32 v239, v43, v35
	s_nop 0
	s_nop 1
	v_permlane32_swap_b32_e32 v236, v238
	v_permlane32_swap_b32_e32 v237, v239
	s_nop 1
	v_permlane16_swap_b32_e32 v236, v238
	v_permlane16_swap_b32_e32 v237, v239
	v_lshl_add_u64 v[242:243], v[40:41], 0, v[240:241]
	s_nop 0
	global_store_dwordx4 v[242:243], v[236:239], off sc1
	s_nop 1
	v_mov_b32_e32 v34, v212
	v_mov_b32_e32 v35, v213
	v_mov_b32_e32 v37, v177
	v_or_b32_e32 v36, 0xa0, v176
	v_lshl_add_u64 v[40:41], v[38:39], 0, s[14:15]
	v_lshl_add_u64 v[36:37], s[92:93], 0, v[36:37]
	v_lshlrev_b32_e32 v42, 16, v34
	v_and_b32_e32 v34, 0xffff0000, v34
	v_lshlrev_b32_e32 v43, 16, v35
	v_and_b32_e32 v35, 0xffff0000, v35
	v_mul_f32_e32 v34, v143, v34
	v_mul_f32_e32 v35, v145, v35
	v_mul_f32_e32 v42, v142, v42
	v_mul_f32_e32 v43, v144, v43
	v_cvt_pk_bf16_f32 v236, v42, v34
	v_cvt_pk_bf16_f32 v237, v43, v35
	s_nop 0
	v_mov_b32_e32 v34, v214
	v_mov_b32_e32 v35, v215
	v_mov_b32_e32 v37, v177
	v_or_b32_e32 v36, 0xc0, v176
	v_lshl_add_u64 v[40:41], v[38:39], 0, s[18:19]
	v_lshl_add_u64 v[36:37], s[92:93], 0, v[36:37]
	v_or_b32_e32 v176, 0xe0, v176
	v_lshlrev_b32_e32 v42, 16, v34
	v_and_b32_e32 v34, 0xffff0000, v34
	v_lshlrev_b32_e32 v43, 16, v35
	v_and_b32_e32 v35, 0xffff0000, v35
	v_mul_f32_e32 v34, v139, v34
	v_mul_f32_e32 v35, v141, v35
	v_mul_f32_e32 v42, v138, v42
	v_mul_f32_e32 v43, v140, v43
	v_cvt_pk_bf16_f32 v238, v42, v34
	v_cvt_pk_bf16_f32 v239, v43, v35
	s_nop 0
	s_nop 1
	v_permlane32_swap_b32_e32 v236, v238
; __device__ __forceinline__ unsigned cvt_pk_bf16(float lo, float hi) { unsigned r; asm volatile("v_cvt_pk_bf16_f32 %0, %1, %2" : "=v"(r) : "v"(lo), "v"(hi)); return r; }
; __device__ __forceinline__ void st_wt8(void* ptr, u32x2 v) { asm volatile("global_store_dwordx2 %0, %1, off sc1" :: "v"(ptr), "v"(v) : "memory"); }
; __device__ __forceinline__ float bf_lo(unsigned w) { return __uint_as_float(w << 16); }
; __device__ __forceinline__ float bf_hi(unsigned w) { return __uint_as_float(w & 0xffff0000u); }
; __device__ __forceinline__ void attn_phase(const Params& p, LAS unsigned char* lds, int cidx) {
;     ...
;         if (active) {
; #pragma unroll
;             for (int mt = 0; mt < 2; ++mt)
; #pragma unroll
;                 for (int dt = 0; dt < 8; ++dt) {
;                     const size_t off = (size_t)(qrow0 + 16 * mt + fr) * DM + h * 128 + 16 * dt + 4 * fq;
;                     const u32x2 zr = __builtin_nontemporal_load((const u32x2*)(sz1 + off)); const f32x4 a = o[mt][dt];
;                     u32x2 w; w.x = cvt_pk_bf16(a[0] * bf_lo(zr.x), a[1] * bf_hi(zr.x)); w.y = cvt_pk_bf16(a[2] * bf_lo(zr.y), a[3] * bf_hi(zr.y));
;                     st_wt8(y1 + off, w);
;                 }
	v_permlane32_swap_b32_e32 v237, v239
	s_nop 1
	v_permlane16_swap_b32_e32 v236, v238
	v_permlane16_swap_b32_e32 v237, v239
	v_lshl_add_u64 v[242:243], v[40:41], 0, v[240:241]
	s_nop 0
	global_store_dwordx4 v[242:243], v[236:239], off sc1
	s_nop 1
	v_mov_b32_e32 v34, v216
	v_mov_b32_e32 v35, v217
	v_lshl_add_u64 v[36:37], v[38:39], 0, s[20:21]
	v_lshl_add_u64 v[40:41], s[92:93], 0, v[176:177]
	v_lshl_add_u64 v[38:39], v[38:39], 0, s[22:23]
	v_lshlrev_b32_e32 v42, 16, v34
	v_and_b32_e32 v34, 0xffff0000, v34
	v_lshlrev_b32_e32 v43, 16, v35
	v_and_b32_e32 v35, 0xffff0000, v35
	v_mul_f32_e32 v34, v135, v34
	v_mul_f32_e32 v35, v137, v35
	v_mul_f32_e32 v42, v134, v42
	v_mul_f32_e32 v43, v136, v43
	v_cvt_pk_bf16_f32 v236, v42, v34
	v_cvt_pk_bf16_f32 v237, v43, v35
	s_nop 0
	v_mov_b32_e32 v34, v218
	v_mov_b32_e32 v35, v219
	v_lshl_add_u64 v[36:37], s[92:93], 0, v[174:175]
	v_lshlrev_b32_e32 v1, 16, v34
	v_and_b32_e32 v34, 0xffff0000, v34
	v_lshlrev_b32_e32 v40, 16, v35
	v_and_b32_e32 v35, 0xffff0000, v35
	v_mul_f32_e32 v34, v115, v34
	v_mul_f32_e32 v35, v117, v35
	v_mul_f32_e32 v1, v114, v1
	v_mul_f32_e32 v40, v116, v40
	v_cvt_pk_bf16_f32 v238, v1, v34
	v_cvt_pk_bf16_f32 v239, v40, v35
	s_nop 0
	s_nop 1
	v_permlane32_swap_b32_e32 v236, v238
	v_permlane32_swap_b32_e32 v237, v239
	s_nop 1
	v_permlane16_swap_b32_e32 v236, v238
	v_permlane16_swap_b32_e32 v237, v239
	v_lshl_add_u64 v[242:243], v[38:39], 0, v[240:241]
	s_nop 0
	global_store_dwordx4 v[242:243], v[236:239], off sc1
	s_nop 1
	v_mov_b32_e32 v34, v220
	v_mov_b32_e32 v35, v221
	v_mov_b32_e32 v37, v175
	v_or_b32_e32 v36, 32, v174
	v_lshl_add_u64 v[38:39], s[2:3], 0, v[174:175]
	v_lshl_add_u64 v[36:37], s[92:93], 0, v[36:37]
	v_lshlrev_b32_e32 v1, 16, v34
	v_and_b32_e32 v34, 0xffff0000, v34
	v_lshlrev_b32_e32 v40, 16, v35
	v_and_b32_e32 v35, 0xffff0000, v35
	v_mul_f32_e32 v34, v95, v34
	v_mul_f32_e32 v35, v97, v35
	v_mul_f32_e32 v1, v94, v1
	v_mul_f32_e32 v40, v96, v40
	v_cvt_pk_bf16_f32 v236, v1, v34
	v_cvt_pk_bf16_f32 v237, v40, v35
	v_lshl_add_u64 v[40:41], v[38:39], 0, 32
	v_mov_b32_e32 v34, v222
	v_mov_b32_e32 v35, v223
	v_mov_b32_e32 v37, v175
	v_or_b32_e32 v36, 64, v174
	v_lshl_add_u64 v[36:37], s[92:93], 0, v[36:37]
	v_lshlrev_b32_e32 v1, 16, v34
	v_and_b32_e32 v34, 0xffff0000, v34
	v_lshlrev_b32_e32 v42, 16, v35
	v_and_b32_e32 v35, 0xffff0000, v35
	v_mul_f32_e32 v34, v91, v34
	v_mul_f32_e32 v35, v93, v35
	v_mul_f32_e32 v1, v90, v1
	v_mul_f32_e32 v42, v92, v42
	v_cvt_pk_bf16_f32 v238, v1, v34
	v_cvt_pk_bf16_f32 v239, v42, v35
	s_nop 0
	s_nop 1
	v_permlane32_swap_b32_e32 v236, v238
	v_permlane32_swap_b32_e32 v237, v239
	s_nop 1
	v_permlane16_swap_b32_e32 v236, v238
	v_permlane16_swap_b32_e32 v237, v239
	v_lshl_add_u64 v[242:243], v[40:41], 0, v[240:241]
	s_nop 0
	global_store_dwordx4 v[242:243], v[236:239], off sc1
	s_nop 1
	v_mov_b32_e32 v34, v224
	v_mov_b32_e32 v35, v225
	v_mov_b32_e32 v37, v175
	v_or_b32_e32 v36, 0x60, v174
	v_lshl_add_u64 v[40:41], v[38:39], 0, 64
	v_lshl_add_u64 v[36:37], s[92:93], 0, v[36:37]
	v_lshlrev_b32_e32 v1, 16, v34
	v_and_b32_e32 v34, 0xffff0000, v34
	v_lshlrev_b32_e32 v42, 16, v35
	v_and_b32_e32 v35, 0xffff0000, v35
	v_mul_f32_e32 v34, v87, v34
	v_mul_f32_e32 v35, v89, v35
	v_mul_f32_e32 v1, v86, v1
	v_mul_f32_e32 v42, v88, v42
	v_cvt_pk_bf16_f32 v236, v1, v34
	v_cvt_pk_bf16_f32 v237, v42, v35
	s_nop 0
	v_mov_b32_e32 v34, v226
	v_mov_b32_e32 v35, v227
	v_mov_b32_e32 v37, v175
	v_or_b32_e32 v36, 0x80, v174
	v_lshl_add_u64 v[40:41], v[38:39], 0, s[6:7]
	v_lshl_add_u64 v[36:37], s[92:93], 0, v[36:37]
	v_lshlrev_b32_e32 v1, 16, v34
	v_and_b32_e32 v34, 0xffff0000, v34
	v_lshlrev_b32_e32 v42, 16, v35
	v_and_b32_e32 v35, 0xffff0000, v35
	v_mul_f32_e32 v34, v83, v34
	v_mul_f32_e32 v35, v85, v35
	v_mul_f32_e32 v1, v82, v1
	v_mul_f32_e32 v42, v84, v42
	v_cvt_pk_bf16_f32 v238, v1, v34
	v_cvt_pk_bf16_f32 v239, v42, v35
	s_nop 0
	s_nop 1
	v_permlane32_swap_b32_e32 v236, v238
	v_permlane32_swap_b32_e32 v237, v239
	s_nop 1
	v_permlane16_swap_b32_e32 v236, v238
	v_permlane16_swap_b32_e32 v237, v239
	v_lshl_add_u64 v[242:243], v[40:41], 0, v[240:241]
	s_nop 0
	global_store_dwordx4 v[242:243], v[236:239], off sc1
	s_nop 1
	v_mov_b32_e32 v34, v228
	v_mov_b32_e32 v35, v229
	v_mov_b32_e32 v37, v175
	v_or_b32_e32 v36, 0xa0, v174
	v_lshl_add_u64 v[40:41], v[38:39], 0, s[14:15]
	v_lshl_add_u64 v[36:37], s[92:93], 0, v[36:37]
	v_lshlrev_b32_e32 v1, 16, v34
	v_and_b32_e32 v34, 0xffff0000, v34
	v_lshlrev_b32_e32 v42, 16, v35
	v_and_b32_e32 v35, 0xffff0000, v35
	v_mul_f32_e32 v34, v79, v34
	v_mul_f32_e32 v35, v81, v35
	v_mul_f32_e32 v1, v78, v1
	v_mul_f32_e32 v42, v80, v42
	v_cvt_pk_bf16_f32 v236, v1, v34
	v_cvt_pk_bf16_f32 v237, v42, v35
	s_nop 0
	v_mov_b32_e32 v34, v230
	v_mov_b32_e32 v35, v231
	v_mov_b32_e32 v37, v175
	v_or_b32_e32 v36, 0xc0, v174
	v_lshl_add_u64 v[40:41], v[38:39], 0, s[18:19]
	v_lshl_add_u64 v[36:37], s[92:93], 0, v[36:37]
	v_or_b32_e32 v174, 0xe0, v174
	v_lshlrev_b32_e32 v1, 16, v34
	v_and_b32_e32 v34, 0xffff0000, v34
	v_lshlrev_b32_e32 v42, 16, v35
	v_and_b32_e32 v35, 0xffff0000, v35
	v_mul_f32_e32 v34, v75, v34
	v_mul_f32_e32 v35, v77, v35
	v_mul_f32_e32 v1, v74, v1
	v_mul_f32_e32 v42, v76, v42
	v_cvt_pk_bf16_f32 v238, v1, v34
	v_cvt_pk_bf16_f32 v239, v42, v35
	s_nop 0
	s_nop 1
	v_permlane32_swap_b32_e32 v236, v238
	v_permlane32_swap_b32_e32 v237, v239
	s_nop 1
	v_permlane16_swap_b32_e32 v236, v238
	v_permlane16_swap_b32_e32 v237, v239
	v_lshl_add_u64 v[242:243], v[40:41], 0, v[240:241]
	s_nop 0
	global_store_dwordx4 v[242:243], v[236:239], off sc1
	s_nop 1
	v_mov_b32_e32 v34, v232
	v_mov_b32_e32 v35, v233
	v_lshl_add_u64 v[36:37], v[38:39], 0, s[20:21]
	v_lshl_add_u64 v[40:41], s[92:93], 0, v[174:175]
	v_lshlrev_b32_e32 v1, 16, v34
	v_and_b32_e32 v34, 0xffff0000, v34
	v_lshlrev_b32_e32 v42, 16, v35
	v_and_b32_e32 v35, 0xffff0000, v35
	v_mul_f32_e32 v34, v71, v34
	v_mul_f32_e32 v35, v73, v35
	v_mul_f32_e32 v1, v70, v1
	v_mul_f32_e32 v42, v72, v42
	v_cvt_pk_bf16_f32 v236, v1, v34
	v_cvt_pk_bf16_f32 v237, v42, v35
	s_nop 0
	v_mov_b32_e32 v34, v192
	v_mov_b32_e32 v35, v193
	v_lshlrev_b32_e32 v1, 16, v34
	v_and_b32_e32 v34, 0xffff0000, v34
	v_lshlrev_b32_e32 v36, 16, v35
	v_and_b32_e32 v35, 0xffff0000, v35
	v_mul_f32_e32 v34, v67, v34
	v_mul_f32_e32 v36, v68, v36
	v_mul_f32_e32 v35, v69, v35
	v_mul_f32_e32 v1, v66, v1
	v_cvt_pk_bf16_f32 v238, v1, v34
	v_cvt_pk_bf16_f32 v239, v36, v35
	v_lshl_add_u64 v[36:37], v[38:39], 0, s[22:23]
	s_nop 1
	v_permlane32_swap_b32_e32 v236, v238
	v_permlane32_swap_b32_e32 v237, v239
	s_nop 1
	v_permlane16_swap_b32_e32 v236, v238
	v_permlane16_swap_b32_e32 v237, v239
	v_lshl_add_u64 v[242:243], v[36:37], 0, v[240:241]
	s_nop 0
	global_store_dwordx4 v[242:243], v[236:239], off sc1
	s_nop 1
